# rmsnorm sample rows (R1,R2,R3): hand-written one-row-per-wave path, partial-slab loads pipelined 4 deep (G==256)
# speedup vs baseline: 1.0239x; 1.0013x over previous
.LBB0_632:
	s_cmpk_gt_i32 s52, 0x23ff
	s_cbranch_scc1 .LBB0_662
	s_cmpk_lg_i32 s26, 0x100
	s_cbranch_scc1 .Lsrow_r1_orig
	s_waitcnt lgkmcnt(0)
	v_and_b32_e32 v195, 63, v164
	v_lshlrev_b32_e32 v162, 4, v195
	v_lshlrev_b32_e32 v163, 5, v195
	v_lshlrev_b32_e32 v243, 2, v195
	v_add_u32_e32 v194, 0x1000, v163
	s_add_i32 s93, s52, 0xffffe000
	s_lshl_b32 s97, s93, 12
	s_add_u32 s98, s34, s97
	s_addc_u32 s99, s35, 0
	s_add_u32 s98, s98, 0x19600000
	s_addc_u32 s99, s99, 0
	s_waitcnt lgkmcnt(0)
	s_lshl_b32 s97, s93, 13
	s_add_u32 s94, s10, s97
	s_addc_u32 s95, s11, 0
	global_load_dwordx4 v[118:121], v163, s[94:95]
	global_load_dwordx4 v[122:125], v163, s[94:95] offset:16
	global_load_dwordx4 v[126:129], v163, s[94:95] offset:2048
	global_load_dwordx4 v[130:133], v163, s[94:95] offset:2064
	global_load_dwordx4 v[134:137], v194, s[94:95]
	global_load_dwordx4 v[138:141], v194, s[94:95] offset:16
	global_load_dwordx4 v[142:145], v194, s[94:95] offset:2048
	global_load_dwordx4 v[146:149], v194, s[94:95] offset:2064
	global_load_dwordx4 v[150:153], v162, s[98:99]
	global_load_dwordx4 v[154:157], v162, s[98:99] offset:1024
	global_load_dwordx4 v[158:161], v162, s[98:99] offset:2048
	global_load_dwordx4 v[166:169], v162, s[98:99] offset:3072
	s_add_u32 s98, s98, 0x400000
	s_addc_u32 s99, s99, 0
	global_load_dwordx4 v[170:173], v162, s[98:99]
	global_load_dwordx4 v[174:177], v162, s[98:99] offset:1024
	global_load_dwordx4 v[178:181], v162, s[98:99] offset:2048
	global_load_dwordx4 v[182:185], v162, s[98:99] offset:3072
	s_add_u32 s98, s98, 0x400000
	s_addc_u32 s99, s99, 0
	global_load_dwordx4 v[186:189], v162, s[98:99]
	global_load_dwordx4 v[190:193], v162, s[98:99] offset:1024
	global_load_dwordx4 v[198:201], v162, s[98:99] offset:2048
	global_load_dwordx4 v[202:205], v162, s[98:99] offset:3072
	s_add_u32 s98, s98, 0x400000
	s_addc_u32 s99, s99, 0
	global_load_dwordx4 v[206:209], v162, s[98:99]
	global_load_dwordx4 v[210:213], v162, s[98:99] offset:1024
	global_load_dwordx4 v[214:217], v162, s[98:99] offset:2048
	global_load_dwordx4 v[218:221], v162, s[98:99] offset:3072
	s_add_u32 s98, s98, 0x400000
	s_addc_u32 s99, s99, 0
	s_waitcnt vmcnt(12)
	v_lshlrev_b32_e32 v195, 16, v150
	v_and_b32_e32 v197, 0xffff0000, v150
	v_add_f32_e32 v118, v118, v195
	v_add_f32_e32 v119, v119, v197
	v_lshlrev_b32_e32 v195, 16, v151
	v_and_b32_e32 v197, 0xffff0000, v151
	v_add_f32_e32 v120, v120, v195
	v_add_f32_e32 v121, v121, v197
	v_lshlrev_b32_e32 v195, 16, v152
	v_and_b32_e32 v197, 0xffff0000, v152
	v_add_f32_e32 v122, v122, v195
	v_add_f32_e32 v123, v123, v197
	v_lshlrev_b32_e32 v195, 16, v153
	v_and_b32_e32 v197, 0xffff0000, v153
	v_add_f32_e32 v124, v124, v195
	v_add_f32_e32 v125, v125, v197
	v_lshlrev_b32_e32 v195, 16, v154
	v_and_b32_e32 v197, 0xffff0000, v154
	v_add_f32_e32 v126, v126, v195
	v_add_f32_e32 v127, v127, v197
	v_lshlrev_b32_e32 v195, 16, v155
	v_and_b32_e32 v197, 0xffff0000, v155
	v_add_f32_e32 v128, v128, v195
	v_add_f32_e32 v129, v129, v197
	v_lshlrev_b32_e32 v195, 16, v156
	v_and_b32_e32 v197, 0xffff0000, v156
	v_add_f32_e32 v130, v130, v195
	v_add_f32_e32 v131, v131, v197
	v_lshlrev_b32_e32 v195, 16, v157
	v_and_b32_e32 v197, 0xffff0000, v157
	v_add_f32_e32 v132, v132, v195
	v_add_f32_e32 v133, v133, v197
	v_lshlrev_b32_e32 v195, 16, v158
	v_and_b32_e32 v197, 0xffff0000, v158
	v_add_f32_e32 v134, v134, v195
	v_add_f32_e32 v135, v135, v197
	v_lshlrev_b32_e32 v195, 16, v159
	v_and_b32_e32 v197, 0xffff0000, v159
	v_add_f32_e32 v136, v136, v195
	v_add_f32_e32 v137, v137, v197
	v_lshlrev_b32_e32 v195, 16, v160
	v_and_b32_e32 v197, 0xffff0000, v160
	v_add_f32_e32 v138, v138, v195
	v_add_f32_e32 v139, v139, v197
	v_lshlrev_b32_e32 v195, 16, v161
	v_and_b32_e32 v197, 0xffff0000, v161
	v_add_f32_e32 v140, v140, v195
	v_add_f32_e32 v141, v141, v197
	v_lshlrev_b32_e32 v195, 16, v166
	v_and_b32_e32 v197, 0xffff0000, v166
	v_add_f32_e32 v142, v142, v195
	v_add_f32_e32 v143, v143, v197
	v_lshlrev_b32_e32 v195, 16, v167
	v_and_b32_e32 v197, 0xffff0000, v167
	v_add_f32_e32 v144, v144, v195
	v_add_f32_e32 v145, v145, v197
	v_lshlrev_b32_e32 v195, 16, v168
	v_and_b32_e32 v197, 0xffff0000, v168
	v_add_f32_e32 v146, v146, v195
	v_add_f32_e32 v147, v147, v197
	v_lshlrev_b32_e32 v195, 16, v169
	v_and_b32_e32 v197, 0xffff0000, v169
	v_add_f32_e32 v148, v148, v195
	v_add_f32_e32 v149, v149, v197
	global_load_dwordx4 v[150:153], v162, s[98:99]
	global_load_dwordx4 v[154:157], v162, s[98:99] offset:1024
	global_load_dwordx4 v[158:161], v162, s[98:99] offset:2048
	global_load_dwordx4 v[166:169], v162, s[98:99] offset:3072
	s_add_u32 s98, s98, 0x400000
	s_addc_u32 s99, s99, 0
	s_waitcnt vmcnt(12)
	v_lshlrev_b32_e32 v195, 16, v170
	v_and_b32_e32 v197, 0xffff0000, v170
	v_add_f32_e32 v118, v118, v195
	v_add_f32_e32 v119, v119, v197
	v_lshlrev_b32_e32 v195, 16, v171
	v_and_b32_e32 v197, 0xffff0000, v171
	v_add_f32_e32 v120, v120, v195
	v_add_f32_e32 v121, v121, v197
	v_lshlrev_b32_e32 v195, 16, v172
	v_and_b32_e32 v197, 0xffff0000, v172
	v_add_f32_e32 v122, v122, v195
	v_add_f32_e32 v123, v123, v197
	v_lshlrev_b32_e32 v195, 16, v173
	v_and_b32_e32 v197, 0xffff0000, v173
	v_add_f32_e32 v124, v124, v195
	v_add_f32_e32 v125, v125, v197
	v_lshlrev_b32_e32 v195, 16, v174
	v_and_b32_e32 v197, 0xffff0000, v174
	v_add_f32_e32 v126, v126, v195
	v_add_f32_e32 v127, v127, v197
	v_lshlrev_b32_e32 v195, 16, v175
	v_and_b32_e32 v197, 0xffff0000, v175
	v_add_f32_e32 v128, v128, v195
	v_add_f32_e32 v129, v129, v197
	v_lshlrev_b32_e32 v195, 16, v176
	v_and_b32_e32 v197, 0xffff0000, v176
	v_add_f32_e32 v130, v130, v195
	v_add_f32_e32 v131, v131, v197
	v_lshlrev_b32_e32 v195, 16, v177
	v_and_b32_e32 v197, 0xffff0000, v177
	v_add_f32_e32 v132, v132, v195
	v_add_f32_e32 v133, v133, v197
	v_lshlrev_b32_e32 v195, 16, v178
	v_and_b32_e32 v197, 0xffff0000, v178
	v_add_f32_e32 v134, v134, v195
	v_add_f32_e32 v135, v135, v197
	v_lshlrev_b32_e32 v195, 16, v179
	v_and_b32_e32 v197, 0xffff0000, v179
	v_add_f32_e32 v136, v136, v195
	v_add_f32_e32 v137, v137, v197
	v_lshlrev_b32_e32 v195, 16, v180
	v_and_b32_e32 v197, 0xffff0000, v180
	v_add_f32_e32 v138, v138, v195
	v_add_f32_e32 v139, v139, v197
	v_lshlrev_b32_e32 v195, 16, v181
	v_and_b32_e32 v197, 0xffff0000, v181
	v_add_f32_e32 v140, v140, v195
	v_add_f32_e32 v141, v141, v197
	v_lshlrev_b32_e32 v195, 16, v182
	v_and_b32_e32 v197, 0xffff0000, v182
	v_add_f32_e32 v142, v142, v195
	v_add_f32_e32 v143, v143, v197
	v_lshlrev_b32_e32 v195, 16, v183
	v_and_b32_e32 v197, 0xffff0000, v183
	v_add_f32_e32 v144, v144, v195
	v_add_f32_e32 v145, v145, v197
	v_lshlrev_b32_e32 v195, 16, v184
	v_and_b32_e32 v197, 0xffff0000, v184
	v_add_f32_e32 v146, v146, v195
	v_add_f32_e32 v147, v147, v197
	v_lshlrev_b32_e32 v195, 16, v185
	v_and_b32_e32 v197, 0xffff0000, v185
	v_add_f32_e32 v148, v148, v195
	v_add_f32_e32 v149, v149, v197
	global_load_dwordx4 v[170:173], v162, s[98:99]
	global_load_dwordx4 v[174:177], v162, s[98:99] offset:1024
	global_load_dwordx4 v[178:181], v162, s[98:99] offset:2048
	global_load_dwordx4 v[182:185], v162, s[98:99] offset:3072
	s_add_u32 s98, s98, 0x400000
	s_addc_u32 s99, s99, 0
	s_waitcnt vmcnt(12)
	v_lshlrev_b32_e32 v195, 16, v186
	v_and_b32_e32 v197, 0xffff0000, v186
	v_add_f32_e32 v118, v118, v195
	v_add_f32_e32 v119, v119, v197
	v_lshlrev_b32_e32 v195, 16, v187
	v_and_b32_e32 v197, 0xffff0000, v187
	v_add_f32_e32 v120, v120, v195
	v_add_f32_e32 v121, v121, v197
	v_lshlrev_b32_e32 v195, 16, v188
	v_and_b32_e32 v197, 0xffff0000, v188
	v_add_f32_e32 v122, v122, v195
	v_add_f32_e32 v123, v123, v197
	v_lshlrev_b32_e32 v195, 16, v189
	v_and_b32_e32 v197, 0xffff0000, v189
	v_add_f32_e32 v124, v124, v195
	v_add_f32_e32 v125, v125, v197
	v_lshlrev_b32_e32 v195, 16, v190
	v_and_b32_e32 v197, 0xffff0000, v190
	v_add_f32_e32 v126, v126, v195
	v_add_f32_e32 v127, v127, v197
	v_lshlrev_b32_e32 v195, 16, v191
	v_and_b32_e32 v197, 0xffff0000, v191
	v_add_f32_e32 v128, v128, v195
	v_add_f32_e32 v129, v129, v197
	v_lshlrev_b32_e32 v195, 16, v192
	v_and_b32_e32 v197, 0xffff0000, v192
	v_add_f32_e32 v130, v130, v195
	v_add_f32_e32 v131, v131, v197
	v_lshlrev_b32_e32 v195, 16, v193
	v_and_b32_e32 v197, 0xffff0000, v193
	v_add_f32_e32 v132, v132, v195
	v_add_f32_e32 v133, v133, v197
	v_lshlrev_b32_e32 v195, 16, v198
	v_and_b32_e32 v197, 0xffff0000, v198
	v_add_f32_e32 v134, v134, v195
	v_add_f32_e32 v135, v135, v197
	v_lshlrev_b32_e32 v195, 16, v199
	v_and_b32_e32 v197, 0xffff0000, v199
	v_add_f32_e32 v136, v136, v195
	v_add_f32_e32 v137, v137, v197
	v_lshlrev_b32_e32 v195, 16, v200
	v_and_b32_e32 v197, 0xffff0000, v200
	v_add_f32_e32 v138, v138, v195
	v_add_f32_e32 v139, v139, v197
	v_lshlrev_b32_e32 v195, 16, v201
	v_and_b32_e32 v197, 0xffff0000, v201
	v_add_f32_e32 v140, v140, v195
	v_add_f32_e32 v141, v141, v197
	v_lshlrev_b32_e32 v195, 16, v202
	v_and_b32_e32 v197, 0xffff0000, v202
	v_add_f32_e32 v142, v142, v195
	v_add_f32_e32 v143, v143, v197
	v_lshlrev_b32_e32 v195, 16, v203
	v_and_b32_e32 v197, 0xffff0000, v203
	v_add_f32_e32 v144, v144, v195
	v_add_f32_e32 v145, v145, v197
	v_lshlrev_b32_e32 v195, 16, v204
	v_and_b32_e32 v197, 0xffff0000, v204
	v_add_f32_e32 v146, v146, v195
	v_add_f32_e32 v147, v147, v197
	v_lshlrev_b32_e32 v195, 16, v205
	v_and_b32_e32 v197, 0xffff0000, v205
	v_add_f32_e32 v148, v148, v195
	v_add_f32_e32 v149, v149, v197
	global_load_dwordx4 v[186:189], v162, s[98:99]
	global_load_dwordx4 v[190:193], v162, s[98:99] offset:1024
	global_load_dwordx4 v[198:201], v162, s[98:99] offset:2048
	global_load_dwordx4 v[202:205], v162, s[98:99] offset:3072
	s_add_u32 s98, s98, 0x400000
	s_addc_u32 s99, s99, 0
	s_waitcnt vmcnt(12)
	v_lshlrev_b32_e32 v195, 16, v206
	v_and_b32_e32 v197, 0xffff0000, v206
	v_add_f32_e32 v118, v118, v195
	v_add_f32_e32 v119, v119, v197
	v_lshlrev_b32_e32 v195, 16, v207
	v_and_b32_e32 v197, 0xffff0000, v207
	v_add_f32_e32 v120, v120, v195
	v_add_f32_e32 v121, v121, v197
	v_lshlrev_b32_e32 v195, 16, v208
	v_and_b32_e32 v197, 0xffff0000, v208
	v_add_f32_e32 v122, v122, v195
	v_add_f32_e32 v123, v123, v197
	v_lshlrev_b32_e32 v195, 16, v209
	v_and_b32_e32 v197, 0xffff0000, v209
	v_add_f32_e32 v124, v124, v195
	v_add_f32_e32 v125, v125, v197
	v_lshlrev_b32_e32 v195, 16, v210
	v_and_b32_e32 v197, 0xffff0000, v210
	v_add_f32_e32 v126, v126, v195
	v_add_f32_e32 v127, v127, v197
	v_lshlrev_b32_e32 v195, 16, v211
	v_and_b32_e32 v197, 0xffff0000, v211
	v_add_f32_e32 v128, v128, v195
	v_add_f32_e32 v129, v129, v197
	v_lshlrev_b32_e32 v195, 16, v212
	v_and_b32_e32 v197, 0xffff0000, v212
	v_add_f32_e32 v130, v130, v195
	v_add_f32_e32 v131, v131, v197
	v_lshlrev_b32_e32 v195, 16, v213
	v_and_b32_e32 v197, 0xffff0000, v213
	v_add_f32_e32 v132, v132, v195
	v_add_f32_e32 v133, v133, v197
	v_lshlrev_b32_e32 v195, 16, v214
	v_and_b32_e32 v197, 0xffff0000, v214
	v_add_f32_e32 v134, v134, v195
	v_add_f32_e32 v135, v135, v197
	v_lshlrev_b32_e32 v195, 16, v215
	v_and_b32_e32 v197, 0xffff0000, v215
	v_add_f32_e32 v136, v136, v195
	v_add_f32_e32 v137, v137, v197
	v_lshlrev_b32_e32 v195, 16, v216
	v_and_b32_e32 v197, 0xffff0000, v216
	v_add_f32_e32 v138, v138, v195
	v_add_f32_e32 v139, v139, v197
	v_lshlrev_b32_e32 v195, 16, v217
	v_and_b32_e32 v197, 0xffff0000, v217
	v_add_f32_e32 v140, v140, v195
	v_add_f32_e32 v141, v141, v197
	v_lshlrev_b32_e32 v195, 16, v218
	v_and_b32_e32 v197, 0xffff0000, v218
	v_add_f32_e32 v142, v142, v195
	v_add_f32_e32 v143, v143, v197
	v_lshlrev_b32_e32 v195, 16, v219
	v_and_b32_e32 v197, 0xffff0000, v219
	v_add_f32_e32 v144, v144, v195
	v_add_f32_e32 v145, v145, v197
	v_lshlrev_b32_e32 v195, 16, v220
	v_and_b32_e32 v197, 0xffff0000, v220
	v_add_f32_e32 v146, v146, v195
	v_add_f32_e32 v147, v147, v197
	v_lshlrev_b32_e32 v195, 16, v221
	v_and_b32_e32 v197, 0xffff0000, v221
	v_add_f32_e32 v148, v148, v195
	v_add_f32_e32 v149, v149, v197
	global_load_dwordx4 v[206:209], v162, s[98:99]
	global_load_dwordx4 v[210:213], v162, s[98:99] offset:1024
	global_load_dwordx4 v[214:217], v162, s[98:99] offset:2048
	global_load_dwordx4 v[218:221], v162, s[98:99] offset:3072
	s_add_u32 s98, s98, 0x400000
	s_addc_u32 s99, s99, 0
	s_waitcnt vmcnt(12)
	v_lshlrev_b32_e32 v195, 16, v150
	v_and_b32_e32 v197, 0xffff0000, v150
	v_add_f32_e32 v118, v118, v195
	v_add_f32_e32 v119, v119, v197
	v_lshlrev_b32_e32 v195, 16, v151
	v_and_b32_e32 v197, 0xffff0000, v151
	v_add_f32_e32 v120, v120, v195
	v_add_f32_e32 v121, v121, v197
	v_lshlrev_b32_e32 v195, 16, v152
	v_and_b32_e32 v197, 0xffff0000, v152
	v_add_f32_e32 v122, v122, v195
	v_add_f32_e32 v123, v123, v197
	v_lshlrev_b32_e32 v195, 16, v153
	v_and_b32_e32 v197, 0xffff0000, v153
	v_add_f32_e32 v124, v124, v195
	v_add_f32_e32 v125, v125, v197
	v_lshlrev_b32_e32 v195, 16, v154
	v_and_b32_e32 v197, 0xffff0000, v154
	v_add_f32_e32 v126, v126, v195
	v_add_f32_e32 v127, v127, v197
	v_lshlrev_b32_e32 v195, 16, v155
	v_and_b32_e32 v197, 0xffff0000, v155
	v_add_f32_e32 v128, v128, v195
	v_add_f32_e32 v129, v129, v197
	v_lshlrev_b32_e32 v195, 16, v156
	v_and_b32_e32 v197, 0xffff0000, v156
	v_add_f32_e32 v130, v130, v195
	v_add_f32_e32 v131, v131, v197
	v_lshlrev_b32_e32 v195, 16, v157
	v_and_b32_e32 v197, 0xffff0000, v157
	v_add_f32_e32 v132, v132, v195
	v_add_f32_e32 v133, v133, v197
	v_lshlrev_b32_e32 v195, 16, v158
	v_and_b32_e32 v197, 0xffff0000, v158
	v_add_f32_e32 v134, v134, v195
	v_add_f32_e32 v135, v135, v197
	v_lshlrev_b32_e32 v195, 16, v159
	v_and_b32_e32 v197, 0xffff0000, v159
	v_add_f32_e32 v136, v136, v195
	v_add_f32_e32 v137, v137, v197
	v_lshlrev_b32_e32 v195, 16, v160
	v_and_b32_e32 v197, 0xffff0000, v160
	v_add_f32_e32 v138, v138, v195
	v_add_f32_e32 v139, v139, v197
	v_lshlrev_b32_e32 v195, 16, v161
	v_and_b32_e32 v197, 0xffff0000, v161
	v_add_f32_e32 v140, v140, v195
	v_add_f32_e32 v141, v141, v197
	v_lshlrev_b32_e32 v195, 16, v166
	v_and_b32_e32 v197, 0xffff0000, v166
	v_add_f32_e32 v142, v142, v195
	v_add_f32_e32 v143, v143, v197
	v_lshlrev_b32_e32 v195, 16, v167
	v_and_b32_e32 v197, 0xffff0000, v167
	v_add_f32_e32 v144, v144, v195
	v_add_f32_e32 v145, v145, v197
	v_lshlrev_b32_e32 v195, 16, v168
	v_and_b32_e32 v197, 0xffff0000, v168
	v_add_f32_e32 v146, v146, v195
	v_add_f32_e32 v147, v147, v197
	v_lshlrev_b32_e32 v195, 16, v169
	v_and_b32_e32 v197, 0xffff0000, v169
	v_add_f32_e32 v148, v148, v195
	v_add_f32_e32 v149, v149, v197
	global_load_dwordx4 v[150:153], v163, s[14:15]
	global_load_dwordx4 v[154:157], v163, s[14:15] offset:16
	global_load_dwordx4 v[158:161], v163, s[14:15] offset:2048
	global_load_dwordx4 v[166:169], v163, s[14:15] offset:2064
	s_waitcnt vmcnt(12)
	v_lshlrev_b32_e32 v195, 16, v170
	v_and_b32_e32 v197, 0xffff0000, v170
	v_add_f32_e32 v118, v118, v195
	v_add_f32_e32 v119, v119, v197
	v_lshlrev_b32_e32 v195, 16, v171
	v_and_b32_e32 v197, 0xffff0000, v171
	v_add_f32_e32 v120, v120, v195
	v_add_f32_e32 v121, v121, v197
	v_lshlrev_b32_e32 v195, 16, v172
	v_and_b32_e32 v197, 0xffff0000, v172
	v_add_f32_e32 v122, v122, v195
	v_add_f32_e32 v123, v123, v197
	v_lshlrev_b32_e32 v195, 16, v173
	v_and_b32_e32 v197, 0xffff0000, v173
	v_add_f32_e32 v124, v124, v195
	v_add_f32_e32 v125, v125, v197
	v_lshlrev_b32_e32 v195, 16, v174
	v_and_b32_e32 v197, 0xffff0000, v174
	v_add_f32_e32 v126, v126, v195
	v_add_f32_e32 v127, v127, v197
	v_lshlrev_b32_e32 v195, 16, v175
	v_and_b32_e32 v197, 0xffff0000, v175
	v_add_f32_e32 v128, v128, v195
	v_add_f32_e32 v129, v129, v197
	v_lshlrev_b32_e32 v195, 16, v176
	v_and_b32_e32 v197, 0xffff0000, v176
	v_add_f32_e32 v130, v130, v195
	v_add_f32_e32 v131, v131, v197
	v_lshlrev_b32_e32 v195, 16, v177
	v_and_b32_e32 v197, 0xffff0000, v177
	v_add_f32_e32 v132, v132, v195
	v_add_f32_e32 v133, v133, v197
	v_lshlrev_b32_e32 v195, 16, v178
	v_and_b32_e32 v197, 0xffff0000, v178
	v_add_f32_e32 v134, v134, v195
	v_add_f32_e32 v135, v135, v197
	v_lshlrev_b32_e32 v195, 16, v179
	v_and_b32_e32 v197, 0xffff0000, v179
	v_add_f32_e32 v136, v136, v195
	v_add_f32_e32 v137, v137, v197
	v_lshlrev_b32_e32 v195, 16, v180
	v_and_b32_e32 v197, 0xffff0000, v180
	v_add_f32_e32 v138, v138, v195
	v_add_f32_e32 v139, v139, v197
	v_lshlrev_b32_e32 v195, 16, v181
	v_and_b32_e32 v197, 0xffff0000, v181
	v_add_f32_e32 v140, v140, v195
	v_add_f32_e32 v141, v141, v197
	v_lshlrev_b32_e32 v195, 16, v182
	v_and_b32_e32 v197, 0xffff0000, v182
	v_add_f32_e32 v142, v142, v195
	v_add_f32_e32 v143, v143, v197
	v_lshlrev_b32_e32 v195, 16, v183
	v_and_b32_e32 v197, 0xffff0000, v183
	v_add_f32_e32 v144, v144, v195
	v_add_f32_e32 v145, v145, v197
	v_lshlrev_b32_e32 v195, 16, v184
	v_and_b32_e32 v197, 0xffff0000, v184
	v_add_f32_e32 v146, v146, v195
	v_add_f32_e32 v147, v147, v197
	v_lshlrev_b32_e32 v195, 16, v185
	v_and_b32_e32 v197, 0xffff0000, v185
	v_add_f32_e32 v148, v148, v195
	v_add_f32_e32 v149, v149, v197
	global_load_dwordx4 v[170:173], v194, s[14:15]
	global_load_dwordx4 v[174:177], v194, s[14:15] offset:16
	global_load_dwordx4 v[178:181], v194, s[14:15] offset:2048
	global_load_dwordx4 v[182:185], v194, s[14:15] offset:2064
	s_waitcnt vmcnt(12)
	v_lshlrev_b32_e32 v195, 16, v186
	v_and_b32_e32 v197, 0xffff0000, v186
	v_add_f32_e32 v118, v118, v195
	v_add_f32_e32 v119, v119, v197
	v_lshlrev_b32_e32 v195, 16, v187
	v_and_b32_e32 v197, 0xffff0000, v187
	v_add_f32_e32 v120, v120, v195
	v_add_f32_e32 v121, v121, v197
	v_lshlrev_b32_e32 v195, 16, v188
	v_and_b32_e32 v197, 0xffff0000, v188
	v_add_f32_e32 v122, v122, v195
	v_add_f32_e32 v123, v123, v197
	v_lshlrev_b32_e32 v195, 16, v189
	v_and_b32_e32 v197, 0xffff0000, v189
	v_add_f32_e32 v124, v124, v195
	v_add_f32_e32 v125, v125, v197
	v_lshlrev_b32_e32 v195, 16, v190
	v_and_b32_e32 v197, 0xffff0000, v190
	v_add_f32_e32 v126, v126, v195
	v_add_f32_e32 v127, v127, v197
	v_lshlrev_b32_e32 v195, 16, v191
	v_and_b32_e32 v197, 0xffff0000, v191
	v_add_f32_e32 v128, v128, v195
	v_add_f32_e32 v129, v129, v197
	v_lshlrev_b32_e32 v195, 16, v192
	v_and_b32_e32 v197, 0xffff0000, v192
	v_add_f32_e32 v130, v130, v195
	v_add_f32_e32 v131, v131, v197
	v_lshlrev_b32_e32 v195, 16, v193
	v_and_b32_e32 v197, 0xffff0000, v193
	v_add_f32_e32 v132, v132, v195
	v_add_f32_e32 v133, v133, v197
	v_lshlrev_b32_e32 v195, 16, v198
	v_and_b32_e32 v197, 0xffff0000, v198
	v_add_f32_e32 v134, v134, v195
	v_add_f32_e32 v135, v135, v197
	v_lshlrev_b32_e32 v195, 16, v199
	v_and_b32_e32 v197, 0xffff0000, v199
	v_add_f32_e32 v136, v136, v195
	v_add_f32_e32 v137, v137, v197
	v_lshlrev_b32_e32 v195, 16, v200
	v_and_b32_e32 v197, 0xffff0000, v200
	v_add_f32_e32 v138, v138, v195
	v_add_f32_e32 v139, v139, v197
	v_lshlrev_b32_e32 v195, 16, v201
	v_and_b32_e32 v197, 0xffff0000, v201
	v_add_f32_e32 v140, v140, v195
	v_add_f32_e32 v141, v141, v197
	v_lshlrev_b32_e32 v195, 16, v202
	v_and_b32_e32 v197, 0xffff0000, v202
	v_add_f32_e32 v142, v142, v195
	v_add_f32_e32 v143, v143, v197
	v_lshlrev_b32_e32 v195, 16, v203
	v_and_b32_e32 v197, 0xffff0000, v203
	v_add_f32_e32 v144, v144, v195
	v_add_f32_e32 v145, v145, v197
	v_lshlrev_b32_e32 v195, 16, v204
	v_and_b32_e32 v197, 0xffff0000, v204
	v_add_f32_e32 v146, v146, v195
	v_add_f32_e32 v147, v147, v197
	v_lshlrev_b32_e32 v195, 16, v205
	v_and_b32_e32 v197, 0xffff0000, v205
	v_add_f32_e32 v148, v148, v195
	v_add_f32_e32 v149, v149, v197
	s_waitcnt vmcnt(8)
	v_lshlrev_b32_e32 v195, 16, v206
	v_and_b32_e32 v197, 0xffff0000, v206
	v_add_f32_e32 v118, v118, v195
	v_add_f32_e32 v119, v119, v197
	v_lshlrev_b32_e32 v195, 16, v207
	v_and_b32_e32 v197, 0xffff0000, v207
	v_add_f32_e32 v120, v120, v195
	v_add_f32_e32 v121, v121, v197
	v_lshlrev_b32_e32 v195, 16, v208
	v_and_b32_e32 v197, 0xffff0000, v208
	v_add_f32_e32 v122, v122, v195
	v_add_f32_e32 v123, v123, v197
	v_lshlrev_b32_e32 v195, 16, v209
	v_and_b32_e32 v197, 0xffff0000, v209
	v_add_f32_e32 v124, v124, v195
	v_add_f32_e32 v125, v125, v197
	v_lshlrev_b32_e32 v195, 16, v210
	v_and_b32_e32 v197, 0xffff0000, v210
	v_add_f32_e32 v126, v126, v195
	v_add_f32_e32 v127, v127, v197
	v_lshlrev_b32_e32 v195, 16, v211
	v_and_b32_e32 v197, 0xffff0000, v211
	v_add_f32_e32 v128, v128, v195
	v_add_f32_e32 v129, v129, v197
	v_lshlrev_b32_e32 v195, 16, v212
	v_and_b32_e32 v197, 0xffff0000, v212
	v_add_f32_e32 v130, v130, v195
	v_add_f32_e32 v131, v131, v197
	v_lshlrev_b32_e32 v195, 16, v213
	v_and_b32_e32 v197, 0xffff0000, v213
	v_add_f32_e32 v132, v132, v195
	v_add_f32_e32 v133, v133, v197
	v_lshlrev_b32_e32 v195, 16, v214
	v_and_b32_e32 v197, 0xffff0000, v214
	v_add_f32_e32 v134, v134, v195
	v_add_f32_e32 v135, v135, v197
	v_lshlrev_b32_e32 v195, 16, v215
	v_and_b32_e32 v197, 0xffff0000, v215
	v_add_f32_e32 v136, v136, v195
	v_add_f32_e32 v137, v137, v197
	v_lshlrev_b32_e32 v195, 16, v216
	v_and_b32_e32 v197, 0xffff0000, v216
	v_add_f32_e32 v138, v138, v195
	v_add_f32_e32 v139, v139, v197
	v_lshlrev_b32_e32 v195, 16, v217
	v_and_b32_e32 v197, 0xffff0000, v217
	v_add_f32_e32 v140, v140, v195
	v_add_f32_e32 v141, v141, v197
	v_lshlrev_b32_e32 v195, 16, v218
	v_and_b32_e32 v197, 0xffff0000, v218
	v_add_f32_e32 v142, v142, v195
	v_add_f32_e32 v143, v143, v197
	v_lshlrev_b32_e32 v195, 16, v219
	v_and_b32_e32 v197, 0xffff0000, v219
	v_add_f32_e32 v144, v144, v195
	v_add_f32_e32 v145, v145, v197
	v_lshlrev_b32_e32 v195, 16, v220
	v_and_b32_e32 v197, 0xffff0000, v220
	v_add_f32_e32 v146, v146, v195
	v_add_f32_e32 v147, v147, v197
	v_lshlrev_b32_e32 v195, 16, v221
	v_and_b32_e32 v197, 0xffff0000, v221
	v_add_f32_e32 v148, v148, v195
	v_add_f32_e32 v149, v149, v197
	s_lshl_b32 s97, s52, 12
	s_add_u32 s94, s34, s97
	s_addc_u32 s95, s35, 0
	s_add_u32 s94, s94, 0x20200000
	s_addc_u32 s95, s95, 0
	v_cvt_pk_bf16_f32 v186, v118, v119
	v_cvt_pk_bf16_f32 v187, v120, v121
	v_cvt_pk_bf16_f32 v188, v122, v123
	v_cvt_pk_bf16_f32 v189, v124, v125
	global_store_dwordx4 v162, v[186:189], s[94:95]
	v_cvt_pk_bf16_f32 v190, v126, v127
	v_cvt_pk_bf16_f32 v191, v128, v129
	v_cvt_pk_bf16_f32 v192, v130, v131
	v_cvt_pk_bf16_f32 v193, v132, v133
	global_store_dwordx4 v162, v[190:193], s[94:95] offset:1024
	v_cvt_pk_bf16_f32 v198, v134, v135
	v_cvt_pk_bf16_f32 v199, v136, v137
	v_cvt_pk_bf16_f32 v200, v138, v139
	v_cvt_pk_bf16_f32 v201, v140, v141
	global_store_dwordx4 v162, v[198:201], s[94:95] offset:2048
	v_cvt_pk_bf16_f32 v202, v142, v143
	v_cvt_pk_bf16_f32 v203, v144, v145
	v_cvt_pk_bf16_f32 v204, v146, v147
	v_cvt_pk_bf16_f32 v205, v148, v149
	global_store_dwordx4 v162, v[202:205], s[94:95] offset:3072
	v_lshlrev_b32_e32 v118, 16, v186
	v_and_b32_e32 v119, 0xffff0000, v186
	v_lshlrev_b32_e32 v120, 16, v187
	v_and_b32_e32 v121, 0xffff0000, v187
	v_lshlrev_b32_e32 v122, 16, v188
	v_and_b32_e32 v123, 0xffff0000, v188
	v_lshlrev_b32_e32 v124, 16, v189
	v_and_b32_e32 v125, 0xffff0000, v189
	v_lshlrev_b32_e32 v126, 16, v190
	v_and_b32_e32 v127, 0xffff0000, v190
	v_lshlrev_b32_e32 v128, 16, v191
	v_and_b32_e32 v129, 0xffff0000, v191
	v_lshlrev_b32_e32 v130, 16, v192
	v_and_b32_e32 v131, 0xffff0000, v192
	v_lshlrev_b32_e32 v132, 16, v193
	v_and_b32_e32 v133, 0xffff0000, v193
	v_lshlrev_b32_e32 v134, 16, v198
	v_and_b32_e32 v135, 0xffff0000, v198
	v_lshlrev_b32_e32 v136, 16, v199
	v_and_b32_e32 v137, 0xffff0000, v199
	v_lshlrev_b32_e32 v138, 16, v200
	v_and_b32_e32 v139, 0xffff0000, v200
	v_lshlrev_b32_e32 v140, 16, v201
	v_and_b32_e32 v141, 0xffff0000, v201
	v_lshlrev_b32_e32 v142, 16, v202
	v_and_b32_e32 v143, 0xffff0000, v202
	v_lshlrev_b32_e32 v144, 16, v203
	v_and_b32_e32 v145, 0xffff0000, v203
	v_lshlrev_b32_e32 v146, 16, v204
	v_and_b32_e32 v147, 0xffff0000, v204
	v_lshlrev_b32_e32 v148, 16, v205
	v_and_b32_e32 v149, 0xffff0000, v205
	v_mul_f32_e32 v227, v118, v118
	v_fmac_f32_e32 v227, v119, v119
	v_fmac_f32_e32 v227, v120, v120
	v_fmac_f32_e32 v227, v121, v121
	v_fmac_f32_e32 v227, v122, v122
	v_fmac_f32_e32 v227, v123, v123
	v_fmac_f32_e32 v227, v124, v124
	v_fmac_f32_e32 v227, v125, v125
	v_fmac_f32_e32 v227, v126, v126
	v_fmac_f32_e32 v227, v127, v127
	v_fmac_f32_e32 v227, v128, v128
	v_fmac_f32_e32 v227, v129, v129
	v_fmac_f32_e32 v227, v130, v130
	v_fmac_f32_e32 v227, v131, v131
	v_fmac_f32_e32 v227, v132, v132
	v_fmac_f32_e32 v227, v133, v133
	v_fmac_f32_e32 v227, v134, v134
	v_fmac_f32_e32 v227, v135, v135
	v_fmac_f32_e32 v227, v136, v136
	v_fmac_f32_e32 v227, v137, v137
	v_fmac_f32_e32 v227, v138, v138
	v_fmac_f32_e32 v227, v139, v139
	v_fmac_f32_e32 v227, v140, v140
	v_fmac_f32_e32 v227, v141, v141
	v_fmac_f32_e32 v227, v142, v142
	v_fmac_f32_e32 v227, v143, v143
	v_fmac_f32_e32 v227, v144, v144
	v_fmac_f32_e32 v227, v145, v145
	v_fmac_f32_e32 v227, v146, v146
	v_fmac_f32_e32 v227, v147, v147
	v_fmac_f32_e32 v227, v148, v148
	v_fmac_f32_e32 v227, v149, v149
	v_xor_b32_e32 v195, 4, v243
	ds_bpermute_b32 v242, v195, v227
	s_waitcnt lgkmcnt(0)
	v_add_f32_e32 v227, v227, v242
	v_xor_b32_e32 v195, 8, v243
	ds_bpermute_b32 v242, v195, v227
	s_waitcnt lgkmcnt(0)
	v_add_f32_e32 v227, v227, v242
	v_xor_b32_e32 v195, 16, v243
	ds_bpermute_b32 v242, v195, v227
	s_waitcnt lgkmcnt(0)
	v_add_f32_e32 v227, v227, v242
	v_xor_b32_e32 v195, 32, v243
	ds_bpermute_b32 v242, v195, v227
	s_waitcnt lgkmcnt(0)
	v_add_f32_e32 v227, v227, v242
	v_xor_b32_e32 v195, 64, v243
	ds_bpermute_b32 v242, v195, v227
	s_waitcnt lgkmcnt(0)
	v_add_f32_e32 v227, v227, v242
	v_xor_b32_e32 v195, 128, v243
	ds_bpermute_b32 v242, v195, v227
	s_waitcnt lgkmcnt(0)
	v_add_f32_e32 v227, v227, v242
	v_mov_b32_e32 v240, 0x3a000000
	v_mov_b32_e32 v241, 0x358637bd
	v_fma_f32 v227, v227, v240, v241
	v_rsq_f32_e32 v227, v227
	s_lshl_b32 s97, s52, 12
	s_add_u32 s100, s34, s97
	s_addc_u32 s101, s35, 0
	s_add_u32 s100, s100, 0x9800000
	s_addc_u32 s101, s101, 0
	s_waitcnt vmcnt(4)
	v_mul_f32_e32 v118, v118, v227
	v_mul_f32_e32 v118, v118, v150
	v_mul_f32_e32 v119, v119, v227
	v_mul_f32_e32 v119, v119, v151
	v_mul_f32_e32 v120, v120, v227
	v_mul_f32_e32 v120, v120, v152
	v_mul_f32_e32 v121, v121, v227
	v_mul_f32_e32 v121, v121, v153
	v_mul_f32_e32 v122, v122, v227
	v_mul_f32_e32 v122, v122, v154
	v_mul_f32_e32 v123, v123, v227
	v_mul_f32_e32 v123, v123, v155
	v_mul_f32_e32 v124, v124, v227
	v_mul_f32_e32 v124, v124, v156
	v_mul_f32_e32 v125, v125, v227
	v_mul_f32_e32 v125, v125, v157
	v_mul_f32_e32 v126, v126, v227
	v_mul_f32_e32 v126, v126, v158
	v_mul_f32_e32 v127, v127, v227
	v_mul_f32_e32 v127, v127, v159
	v_mul_f32_e32 v128, v128, v227
	v_mul_f32_e32 v128, v128, v160
	v_mul_f32_e32 v129, v129, v227
	v_mul_f32_e32 v129, v129, v161
	v_mul_f32_e32 v130, v130, v227
	v_mul_f32_e32 v130, v130, v166
	v_mul_f32_e32 v131, v131, v227
	v_mul_f32_e32 v131, v131, v167
	v_mul_f32_e32 v132, v132, v227
	v_mul_f32_e32 v132, v132, v168
	v_mul_f32_e32 v133, v133, v227
	v_mul_f32_e32 v133, v133, v169
	v_mul_f32_e32 v134, v134, v227
	v_mul_f32_e32 v134, v134, v170
	v_mul_f32_e32 v135, v135, v227
	v_mul_f32_e32 v135, v135, v171
	v_mul_f32_e32 v136, v136, v227
	v_mul_f32_e32 v136, v136, v172
	v_mul_f32_e32 v137, v137, v227
	v_mul_f32_e32 v137, v137, v173
	v_mul_f32_e32 v138, v138, v227
	v_mul_f32_e32 v138, v138, v174
	v_mul_f32_e32 v139, v139, v227
	v_mul_f32_e32 v139, v139, v175
	v_mul_f32_e32 v140, v140, v227
	v_mul_f32_e32 v140, v140, v176
	v_mul_f32_e32 v141, v141, v227
	v_mul_f32_e32 v141, v141, v177
	v_mul_f32_e32 v142, v142, v227
	v_mul_f32_e32 v142, v142, v178
	v_mul_f32_e32 v143, v143, v227
	v_mul_f32_e32 v143, v143, v179
	v_mul_f32_e32 v144, v144, v227
	v_mul_f32_e32 v144, v144, v180
	v_mul_f32_e32 v145, v145, v227
	v_mul_f32_e32 v145, v145, v181
	v_mul_f32_e32 v146, v146, v227
	v_mul_f32_e32 v146, v146, v182
	v_mul_f32_e32 v147, v147, v227
	v_mul_f32_e32 v147, v147, v183
	v_mul_f32_e32 v148, v148, v227
	v_mul_f32_e32 v148, v148, v184
	v_mul_f32_e32 v149, v149, v227
	v_mul_f32_e32 v149, v149, v185
	v_cvt_pk_bf16_f32 v206, v118, v119
	v_cvt_pk_bf16_f32 v207, v120, v121
	v_cvt_pk_bf16_f32 v208, v122, v123
	v_cvt_pk_bf16_f32 v209, v124, v125
	global_store_dwordx4 v162, v[206:209], s[100:101]
	v_cvt_pk_bf16_f32 v210, v126, v127
	v_cvt_pk_bf16_f32 v211, v128, v129
	v_cvt_pk_bf16_f32 v212, v130, v131
	v_cvt_pk_bf16_f32 v213, v132, v133
	global_store_dwordx4 v162, v[210:213], s[100:101] offset:1024
	v_cvt_pk_bf16_f32 v214, v134, v135
	v_cvt_pk_bf16_f32 v215, v136, v137
	v_cvt_pk_bf16_f32 v216, v138, v139
	v_cvt_pk_bf16_f32 v217, v140, v141
	global_store_dwordx4 v162, v[214:217], s[100:101] offset:2048
	v_cvt_pk_bf16_f32 v218, v142, v143
	v_cvt_pk_bf16_f32 v219, v144, v145
	v_cvt_pk_bf16_f32 v220, v146, v147
	v_cvt_pk_bf16_f32 v221, v148, v149
	global_store_dwordx4 v162, v[218:221], s[100:101] offset:3072
	s_branch .LBB0_662
.Lsrow_r1_orig:
	s_add_u32 s3, s34, 0x19600000
	s_addc_u32 s12, s35, 0
	s_and_b64 s[40:41], s[38:39], exec
	s_cselect_b32 s41, 0, s12
	s_cselect_b32 s40, 0, s3
	v_lshlrev_b32_e32 v0, 3, v45
	s_waitcnt lgkmcnt(0)
	s_cmp_lg_u64 s[10:11], 0
	s_cselect_b64 s[44:45], -1, 0
	v_mov_b32_e32 v41, 0
	v_or_b32_e32 v4, 0x400, v0
	s_cmp_gt_i32 s26, -1
	v_lshl_add_u64 v[42:43], s[8:9], 0, v[40:41]
	v_lshlrev_b32_e32 v6, 2, v4
	v_mov_b32_e32 v7, v41
	s_cselect_b64 s[8:9], -1, 0
	v_lshl_add_u64 v[2:3], s[34:35], 0, v[40:41]
	v_lshl_add_u64 v[46:47], s[14:15], 0, v[6:7]
	v_or_b32_e32 v6, 0x600, v0
	v_lshl_add_u64 v[50:51], s[6:7], 0, v[40:41]
	s_mov_b64 s[6:7], 0x20200000
	v_cndmask_b32_e64 v1, 0, 1, s[8:9]
	v_lshl_add_u64 v[36:37], s[40:41], 0, v[40:41]
	s_mov_b64 s[40:41], 0x22200000
	v_mov_b32_e32 v45, v41
	v_lshlrev_b32_e32 v8, 2, v6
	v_mov_b32_e32 v9, v41
	v_lshl_add_u64 v[52:53], v[2:3], 0, s[6:7]
	s_ashr_i32 s19, s18, 31
	v_cmp_ne_u32_e64 s[6:7], 1, v1
	v_cndmask_b32_e64 v1, 0, 1, s[44:45]
	s_mov_b32 s13, 0
	v_lshl_add_u64 v[38:39], v[2:3], 0, s[40:41]
	v_lshl_add_u64 v[44:45], s[14:15], 0, v[44:45]
	v_lshl_add_u64 v[48:49], s[14:15], 0, v[8:9]
	s_lshl_b64 s[14:15], s[18:19], 12
	v_cmp_ne_u32_e64 s[8:9], 1, v1
	v_lshlrev_b32_e32 v55, 2, v4
	v_lshlrev_b32_e32 v94, 2, v6
	s_mov_b32 s3, 0x400000
	s_mov_b32 s19, 0x800000
	s_mov_b32 s25, 0xc00000
	s_mov_b32 s29, 0x1000000
	s_mov_b32 s45, 0x1400000
	s_mov_b32 s60, 0x1800000
	s_mov_b32 s61, 0x1c00000
	v_mov_b32_e32 v54, 0x358637bd
	s_mov_b32 s44, 0x3a000000
	s_mov_b32 s62, 0xe9600000
	s_mov_b32 s63, 0xe9600400
	s_mov_b32 s64, 0xe9600800
	s_xor_b64 s[46:47], s[38:39], -1
	v_lshlrev_b32_e32 v95, 2, v0
	v_lshlrev_b32_e32 v40, 1, v0
	v_mbcnt_hi_u32_b32 v96, -1, v165
	s_branch .LBB0_635

.LBB0_1028:
	s_cmpk_gt_i32 s48, 0x23ff
	s_cbranch_scc1 .LBB0_1042
	s_cmpk_lg_i32 s26, 0x100
	s_cbranch_scc1 .Lsrow_r2_orig
	s_waitcnt lgkmcnt(0)
	v_and_b32_e32 v195, 63, v164
	v_lshlrev_b32_e32 v162, 4, v195
	v_lshlrev_b32_e32 v163, 5, v195
	v_lshlrev_b32_e32 v243, 2, v195
	v_add_u32_e32 v194, 0x1000, v163
	s_add_i32 s93, s48, 0xffffe000
	s_lshl_b32 s97, s93, 12
	s_add_u32 s98, s34, s97
	s_addc_u32 s99, s35, 0
	s_add_u32 s98, s98, 0x19600000
	s_addc_u32 s99, s99, 0
	s_lshl_b32 s97, s48, 12
	s_add_u32 s94, s34, s97
	s_addc_u32 s95, s35, 0
	s_add_u32 s94, s94, 0x20200000
	s_addc_u32 s95, s95, 0
	global_load_dwordx4 v[222:225], v162, s[94:95]
	global_load_dwordx4 v[228:231], v162, s[94:95] offset:1024
	global_load_dwordx4 v[232:235], v162, s[94:95] offset:2048
	global_load_dwordx4 v[236:239], v162, s[94:95] offset:3072
	global_load_dwordx4 v[150:153], v162, s[98:99]
	global_load_dwordx4 v[154:157], v162, s[98:99] offset:1024
	global_load_dwordx4 v[158:161], v162, s[98:99] offset:2048
	global_load_dwordx4 v[166:169], v162, s[98:99] offset:3072
	s_add_u32 s98, s98, 0x400000
	s_addc_u32 s99, s99, 0
	global_load_dwordx4 v[170:173], v162, s[98:99]
	global_load_dwordx4 v[174:177], v162, s[98:99] offset:1024
	global_load_dwordx4 v[178:181], v162, s[98:99] offset:2048
	global_load_dwordx4 v[182:185], v162, s[98:99] offset:3072
	s_add_u32 s98, s98, 0x400000
	s_addc_u32 s99, s99, 0
	global_load_dwordx4 v[186:189], v162, s[98:99]
	global_load_dwordx4 v[190:193], v162, s[98:99] offset:1024
	global_load_dwordx4 v[198:201], v162, s[98:99] offset:2048
	global_load_dwordx4 v[202:205], v162, s[98:99] offset:3072
	s_add_u32 s98, s98, 0x400000
	s_addc_u32 s99, s99, 0
	global_load_dwordx4 v[206:209], v162, s[98:99]
	global_load_dwordx4 v[210:213], v162, s[98:99] offset:1024
	global_load_dwordx4 v[214:217], v162, s[98:99] offset:2048
	global_load_dwordx4 v[218:221], v162, s[98:99] offset:3072
	s_add_u32 s98, s98, 0x400000
	s_addc_u32 s99, s99, 0
	s_waitcnt vmcnt(16)
	v_lshlrev_b32_e32 v118, 16, v222
	v_and_b32_e32 v119, 0xffff0000, v222
	v_lshlrev_b32_e32 v120, 16, v223
	v_and_b32_e32 v121, 0xffff0000, v223
	v_lshlrev_b32_e32 v122, 16, v224
	v_and_b32_e32 v123, 0xffff0000, v224
	v_lshlrev_b32_e32 v124, 16, v225
	v_and_b32_e32 v125, 0xffff0000, v225
	v_lshlrev_b32_e32 v126, 16, v228
	v_and_b32_e32 v127, 0xffff0000, v228
	v_lshlrev_b32_e32 v128, 16, v229
	v_and_b32_e32 v129, 0xffff0000, v229
	v_lshlrev_b32_e32 v130, 16, v230
	v_and_b32_e32 v131, 0xffff0000, v230
	v_lshlrev_b32_e32 v132, 16, v231
	v_and_b32_e32 v133, 0xffff0000, v231
	v_lshlrev_b32_e32 v134, 16, v232
	v_and_b32_e32 v135, 0xffff0000, v232
	v_lshlrev_b32_e32 v136, 16, v233
	v_and_b32_e32 v137, 0xffff0000, v233
	v_lshlrev_b32_e32 v138, 16, v234
	v_and_b32_e32 v139, 0xffff0000, v234
	v_lshlrev_b32_e32 v140, 16, v235
	v_and_b32_e32 v141, 0xffff0000, v235
	v_lshlrev_b32_e32 v142, 16, v236
	v_and_b32_e32 v143, 0xffff0000, v236
	v_lshlrev_b32_e32 v144, 16, v237
	v_and_b32_e32 v145, 0xffff0000, v237
	v_lshlrev_b32_e32 v146, 16, v238
	v_and_b32_e32 v147, 0xffff0000, v238
	v_lshlrev_b32_e32 v148, 16, v239
	v_and_b32_e32 v149, 0xffff0000, v239
	s_waitcnt vmcnt(12)
	v_lshlrev_b32_e32 v195, 16, v150
	v_and_b32_e32 v197, 0xffff0000, v150
	v_add_f32_e32 v118, v118, v195
	v_add_f32_e32 v119, v119, v197
	v_lshlrev_b32_e32 v195, 16, v151
	v_and_b32_e32 v197, 0xffff0000, v151
	v_add_f32_e32 v120, v120, v195
	v_add_f32_e32 v121, v121, v197
	v_lshlrev_b32_e32 v195, 16, v152
	v_and_b32_e32 v197, 0xffff0000, v152
	v_add_f32_e32 v122, v122, v195
	v_add_f32_e32 v123, v123, v197
	v_lshlrev_b32_e32 v195, 16, v153
	v_and_b32_e32 v197, 0xffff0000, v153
	v_add_f32_e32 v124, v124, v195
	v_add_f32_e32 v125, v125, v197
	v_lshlrev_b32_e32 v195, 16, v154
	v_and_b32_e32 v197, 0xffff0000, v154
	v_add_f32_e32 v126, v126, v195
	v_add_f32_e32 v127, v127, v197
	v_lshlrev_b32_e32 v195, 16, v155
	v_and_b32_e32 v197, 0xffff0000, v155
	v_add_f32_e32 v128, v128, v195
	v_add_f32_e32 v129, v129, v197
	v_lshlrev_b32_e32 v195, 16, v156
	v_and_b32_e32 v197, 0xffff0000, v156
	v_add_f32_e32 v130, v130, v195
	v_add_f32_e32 v131, v131, v197
	v_lshlrev_b32_e32 v195, 16, v157
	v_and_b32_e32 v197, 0xffff0000, v157
	v_add_f32_e32 v132, v132, v195
	v_add_f32_e32 v133, v133, v197
	v_lshlrev_b32_e32 v195, 16, v158
	v_and_b32_e32 v197, 0xffff0000, v158
	v_add_f32_e32 v134, v134, v195
	v_add_f32_e32 v135, v135, v197
	v_lshlrev_b32_e32 v195, 16, v159
	v_and_b32_e32 v197, 0xffff0000, v159
	v_add_f32_e32 v136, v136, v195
	v_add_f32_e32 v137, v137, v197
	v_lshlrev_b32_e32 v195, 16, v160
	v_and_b32_e32 v197, 0xffff0000, v160
	v_add_f32_e32 v138, v138, v195
	v_add_f32_e32 v139, v139, v197
	v_lshlrev_b32_e32 v195, 16, v161
	v_and_b32_e32 v197, 0xffff0000, v161
	v_add_f32_e32 v140, v140, v195
	v_add_f32_e32 v141, v141, v197
	v_lshlrev_b32_e32 v195, 16, v166
	v_and_b32_e32 v197, 0xffff0000, v166
	v_add_f32_e32 v142, v142, v195
	v_add_f32_e32 v143, v143, v197
	v_lshlrev_b32_e32 v195, 16, v167
	v_and_b32_e32 v197, 0xffff0000, v167
	v_add_f32_e32 v144, v144, v195
	v_add_f32_e32 v145, v145, v197
	v_lshlrev_b32_e32 v195, 16, v168
	v_and_b32_e32 v197, 0xffff0000, v168
	v_add_f32_e32 v146, v146, v195
	v_add_f32_e32 v147, v147, v197
	v_lshlrev_b32_e32 v195, 16, v169
	v_and_b32_e32 v197, 0xffff0000, v169
	v_add_f32_e32 v148, v148, v195
	v_add_f32_e32 v149, v149, v197
	global_load_dwordx4 v[150:153], v162, s[98:99]
	global_load_dwordx4 v[154:157], v162, s[98:99] offset:1024
	global_load_dwordx4 v[158:161], v162, s[98:99] offset:2048
	global_load_dwordx4 v[166:169], v162, s[98:99] offset:3072
	s_add_u32 s98, s98, 0x400000
	s_addc_u32 s99, s99, 0
	s_waitcnt vmcnt(12)
	v_lshlrev_b32_e32 v195, 16, v170
	v_and_b32_e32 v197, 0xffff0000, v170
	v_add_f32_e32 v118, v118, v195
	v_add_f32_e32 v119, v119, v197
	v_lshlrev_b32_e32 v195, 16, v171
	v_and_b32_e32 v197, 0xffff0000, v171
	v_add_f32_e32 v120, v120, v195
	v_add_f32_e32 v121, v121, v197
	v_lshlrev_b32_e32 v195, 16, v172
	v_and_b32_e32 v197, 0xffff0000, v172
	v_add_f32_e32 v122, v122, v195
	v_add_f32_e32 v123, v123, v197
	v_lshlrev_b32_e32 v195, 16, v173
	v_and_b32_e32 v197, 0xffff0000, v173
	v_add_f32_e32 v124, v124, v195
	v_add_f32_e32 v125, v125, v197
	v_lshlrev_b32_e32 v195, 16, v174
	v_and_b32_e32 v197, 0xffff0000, v174
	v_add_f32_e32 v126, v126, v195
	v_add_f32_e32 v127, v127, v197
	v_lshlrev_b32_e32 v195, 16, v175
	v_and_b32_e32 v197, 0xffff0000, v175
	v_add_f32_e32 v128, v128, v195
	v_add_f32_e32 v129, v129, v197
	v_lshlrev_b32_e32 v195, 16, v176
	v_and_b32_e32 v197, 0xffff0000, v176
	v_add_f32_e32 v130, v130, v195
	v_add_f32_e32 v131, v131, v197
	v_lshlrev_b32_e32 v195, 16, v177
	v_and_b32_e32 v197, 0xffff0000, v177
	v_add_f32_e32 v132, v132, v195
	v_add_f32_e32 v133, v133, v197
	v_lshlrev_b32_e32 v195, 16, v178
	v_and_b32_e32 v197, 0xffff0000, v178
	v_add_f32_e32 v134, v134, v195
	v_add_f32_e32 v135, v135, v197
	v_lshlrev_b32_e32 v195, 16, v179
	v_and_b32_e32 v197, 0xffff0000, v179
	v_add_f32_e32 v136, v136, v195
	v_add_f32_e32 v137, v137, v197
	v_lshlrev_b32_e32 v195, 16, v180
	v_and_b32_e32 v197, 0xffff0000, v180
	v_add_f32_e32 v138, v138, v195
	v_add_f32_e32 v139, v139, v197
	v_lshlrev_b32_e32 v195, 16, v181
	v_and_b32_e32 v197, 0xffff0000, v181
	v_add_f32_e32 v140, v140, v195
	v_add_f32_e32 v141, v141, v197
	v_lshlrev_b32_e32 v195, 16, v182
	v_and_b32_e32 v197, 0xffff0000, v182
	v_add_f32_e32 v142, v142, v195
	v_add_f32_e32 v143, v143, v197
	v_lshlrev_b32_e32 v195, 16, v183
	v_and_b32_e32 v197, 0xffff0000, v183
	v_add_f32_e32 v144, v144, v195
	v_add_f32_e32 v145, v145, v197
	v_lshlrev_b32_e32 v195, 16, v184
	v_and_b32_e32 v197, 0xffff0000, v184
	v_add_f32_e32 v146, v146, v195
	v_add_f32_e32 v147, v147, v197
	v_lshlrev_b32_e32 v195, 16, v185
	v_and_b32_e32 v197, 0xffff0000, v185
	v_add_f32_e32 v148, v148, v195
	v_add_f32_e32 v149, v149, v197
	global_load_dwordx4 v[170:173], v162, s[98:99]
	global_load_dwordx4 v[174:177], v162, s[98:99] offset:1024
	global_load_dwordx4 v[178:181], v162, s[98:99] offset:2048
	global_load_dwordx4 v[182:185], v162, s[98:99] offset:3072
	s_add_u32 s98, s98, 0x400000
	s_addc_u32 s99, s99, 0
	s_waitcnt vmcnt(12)
	v_lshlrev_b32_e32 v195, 16, v186
	v_and_b32_e32 v197, 0xffff0000, v186
	v_add_f32_e32 v118, v118, v195
	v_add_f32_e32 v119, v119, v197
	v_lshlrev_b32_e32 v195, 16, v187
	v_and_b32_e32 v197, 0xffff0000, v187
	v_add_f32_e32 v120, v120, v195
	v_add_f32_e32 v121, v121, v197
	v_lshlrev_b32_e32 v195, 16, v188
	v_and_b32_e32 v197, 0xffff0000, v188
	v_add_f32_e32 v122, v122, v195
	v_add_f32_e32 v123, v123, v197
	v_lshlrev_b32_e32 v195, 16, v189
	v_and_b32_e32 v197, 0xffff0000, v189
	v_add_f32_e32 v124, v124, v195
	v_add_f32_e32 v125, v125, v197
	v_lshlrev_b32_e32 v195, 16, v190
	v_and_b32_e32 v197, 0xffff0000, v190
	v_add_f32_e32 v126, v126, v195
	v_add_f32_e32 v127, v127, v197
	v_lshlrev_b32_e32 v195, 16, v191
	v_and_b32_e32 v197, 0xffff0000, v191
	v_add_f32_e32 v128, v128, v195
	v_add_f32_e32 v129, v129, v197
	v_lshlrev_b32_e32 v195, 16, v192
	v_and_b32_e32 v197, 0xffff0000, v192
	v_add_f32_e32 v130, v130, v195
	v_add_f32_e32 v131, v131, v197
	v_lshlrev_b32_e32 v195, 16, v193
	v_and_b32_e32 v197, 0xffff0000, v193
	v_add_f32_e32 v132, v132, v195
	v_add_f32_e32 v133, v133, v197
	v_lshlrev_b32_e32 v195, 16, v198
	v_and_b32_e32 v197, 0xffff0000, v198
	v_add_f32_e32 v134, v134, v195
	v_add_f32_e32 v135, v135, v197
	v_lshlrev_b32_e32 v195, 16, v199
	v_and_b32_e32 v197, 0xffff0000, v199
	v_add_f32_e32 v136, v136, v195
	v_add_f32_e32 v137, v137, v197
	v_lshlrev_b32_e32 v195, 16, v200
	v_and_b32_e32 v197, 0xffff0000, v200
	v_add_f32_e32 v138, v138, v195
	v_add_f32_e32 v139, v139, v197
	v_lshlrev_b32_e32 v195, 16, v201
	v_and_b32_e32 v197, 0xffff0000, v201
	v_add_f32_e32 v140, v140, v195
	v_add_f32_e32 v141, v141, v197
	v_lshlrev_b32_e32 v195, 16, v202
	v_and_b32_e32 v197, 0xffff0000, v202
	v_add_f32_e32 v142, v142, v195
	v_add_f32_e32 v143, v143, v197
	v_lshlrev_b32_e32 v195, 16, v203
	v_and_b32_e32 v197, 0xffff0000, v203
	v_add_f32_e32 v144, v144, v195
	v_add_f32_e32 v145, v145, v197
	v_lshlrev_b32_e32 v195, 16, v204
	v_and_b32_e32 v197, 0xffff0000, v204
	v_add_f32_e32 v146, v146, v195
	v_add_f32_e32 v147, v147, v197
	v_lshlrev_b32_e32 v195, 16, v205
	v_and_b32_e32 v197, 0xffff0000, v205
	v_add_f32_e32 v148, v148, v195
	v_add_f32_e32 v149, v149, v197
	global_load_dwordx4 v[186:189], v162, s[98:99]
	global_load_dwordx4 v[190:193], v162, s[98:99] offset:1024
	global_load_dwordx4 v[198:201], v162, s[98:99] offset:2048
	global_load_dwordx4 v[202:205], v162, s[98:99] offset:3072
	s_add_u32 s98, s98, 0x400000
	s_addc_u32 s99, s99, 0
	s_waitcnt vmcnt(12)
	v_lshlrev_b32_e32 v195, 16, v206
	v_and_b32_e32 v197, 0xffff0000, v206
	v_add_f32_e32 v118, v118, v195
	v_add_f32_e32 v119, v119, v197
	v_lshlrev_b32_e32 v195, 16, v207
	v_and_b32_e32 v197, 0xffff0000, v207
	v_add_f32_e32 v120, v120, v195
	v_add_f32_e32 v121, v121, v197
	v_lshlrev_b32_e32 v195, 16, v208
	v_and_b32_e32 v197, 0xffff0000, v208
	v_add_f32_e32 v122, v122, v195
	v_add_f32_e32 v123, v123, v197
	v_lshlrev_b32_e32 v195, 16, v209
	v_and_b32_e32 v197, 0xffff0000, v209
	v_add_f32_e32 v124, v124, v195
	v_add_f32_e32 v125, v125, v197
	v_lshlrev_b32_e32 v195, 16, v210
	v_and_b32_e32 v197, 0xffff0000, v210
	v_add_f32_e32 v126, v126, v195
	v_add_f32_e32 v127, v127, v197
	v_lshlrev_b32_e32 v195, 16, v211
	v_and_b32_e32 v197, 0xffff0000, v211
	v_add_f32_e32 v128, v128, v195
	v_add_f32_e32 v129, v129, v197
	v_lshlrev_b32_e32 v195, 16, v212
	v_and_b32_e32 v197, 0xffff0000, v212
	v_add_f32_e32 v130, v130, v195
	v_add_f32_e32 v131, v131, v197
	v_lshlrev_b32_e32 v195, 16, v213
	v_and_b32_e32 v197, 0xffff0000, v213
	v_add_f32_e32 v132, v132, v195
	v_add_f32_e32 v133, v133, v197
	v_lshlrev_b32_e32 v195, 16, v214
	v_and_b32_e32 v197, 0xffff0000, v214
	v_add_f32_e32 v134, v134, v195
	v_add_f32_e32 v135, v135, v197
	v_lshlrev_b32_e32 v195, 16, v215
	v_and_b32_e32 v197, 0xffff0000, v215
	v_add_f32_e32 v136, v136, v195
	v_add_f32_e32 v137, v137, v197
	v_lshlrev_b32_e32 v195, 16, v216
	v_and_b32_e32 v197, 0xffff0000, v216
	v_add_f32_e32 v138, v138, v195
	v_add_f32_e32 v139, v139, v197
	v_lshlrev_b32_e32 v195, 16, v217
	v_and_b32_e32 v197, 0xffff0000, v217
	v_add_f32_e32 v140, v140, v195
	v_add_f32_e32 v141, v141, v197
	v_lshlrev_b32_e32 v195, 16, v218
	v_and_b32_e32 v197, 0xffff0000, v218
	v_add_f32_e32 v142, v142, v195
	v_add_f32_e32 v143, v143, v197
	v_lshlrev_b32_e32 v195, 16, v219
	v_and_b32_e32 v197, 0xffff0000, v219
	v_add_f32_e32 v144, v144, v195
	v_add_f32_e32 v145, v145, v197
	v_lshlrev_b32_e32 v195, 16, v220
	v_and_b32_e32 v197, 0xffff0000, v220
	v_add_f32_e32 v146, v146, v195
	v_add_f32_e32 v147, v147, v197
	v_lshlrev_b32_e32 v195, 16, v221
	v_and_b32_e32 v197, 0xffff0000, v221
	v_add_f32_e32 v148, v148, v195
	v_add_f32_e32 v149, v149, v197
	global_load_dwordx4 v[206:209], v162, s[98:99]
	global_load_dwordx4 v[210:213], v162, s[98:99] offset:1024
	global_load_dwordx4 v[214:217], v162, s[98:99] offset:2048
	global_load_dwordx4 v[218:221], v162, s[98:99] offset:3072
	s_add_u32 s98, s98, 0x400000
	s_addc_u32 s99, s99, 0
	s_waitcnt vmcnt(12)
	v_lshlrev_b32_e32 v195, 16, v150
	v_and_b32_e32 v197, 0xffff0000, v150
	v_add_f32_e32 v118, v118, v195
	v_add_f32_e32 v119, v119, v197
	v_lshlrev_b32_e32 v195, 16, v151
	v_and_b32_e32 v197, 0xffff0000, v151
	v_add_f32_e32 v120, v120, v195
	v_add_f32_e32 v121, v121, v197
	v_lshlrev_b32_e32 v195, 16, v152
	v_and_b32_e32 v197, 0xffff0000, v152
	v_add_f32_e32 v122, v122, v195
	v_add_f32_e32 v123, v123, v197
	v_lshlrev_b32_e32 v195, 16, v153
	v_and_b32_e32 v197, 0xffff0000, v153
	v_add_f32_e32 v124, v124, v195
	v_add_f32_e32 v125, v125, v197
	v_lshlrev_b32_e32 v195, 16, v154
	v_and_b32_e32 v197, 0xffff0000, v154
	v_add_f32_e32 v126, v126, v195
	v_add_f32_e32 v127, v127, v197
	v_lshlrev_b32_e32 v195, 16, v155
	v_and_b32_e32 v197, 0xffff0000, v155
	v_add_f32_e32 v128, v128, v195
	v_add_f32_e32 v129, v129, v197
	v_lshlrev_b32_e32 v195, 16, v156
	v_and_b32_e32 v197, 0xffff0000, v156
	v_add_f32_e32 v130, v130, v195
	v_add_f32_e32 v131, v131, v197
	v_lshlrev_b32_e32 v195, 16, v157
	v_and_b32_e32 v197, 0xffff0000, v157
	v_add_f32_e32 v132, v132, v195
	v_add_f32_e32 v133, v133, v197
	v_lshlrev_b32_e32 v195, 16, v158
	v_and_b32_e32 v197, 0xffff0000, v158
	v_add_f32_e32 v134, v134, v195
	v_add_f32_e32 v135, v135, v197
	v_lshlrev_b32_e32 v195, 16, v159
	v_and_b32_e32 v197, 0xffff0000, v159
	v_add_f32_e32 v136, v136, v195
	v_add_f32_e32 v137, v137, v197
	v_lshlrev_b32_e32 v195, 16, v160
	v_and_b32_e32 v197, 0xffff0000, v160
	v_add_f32_e32 v138, v138, v195
	v_add_f32_e32 v139, v139, v197
	v_lshlrev_b32_e32 v195, 16, v161
	v_and_b32_e32 v197, 0xffff0000, v161
	v_add_f32_e32 v140, v140, v195
	v_add_f32_e32 v141, v141, v197
	v_lshlrev_b32_e32 v195, 16, v166
	v_and_b32_e32 v197, 0xffff0000, v166
	v_add_f32_e32 v142, v142, v195
	v_add_f32_e32 v143, v143, v197
	v_lshlrev_b32_e32 v195, 16, v167
	v_and_b32_e32 v197, 0xffff0000, v167
	v_add_f32_e32 v144, v144, v195
	v_add_f32_e32 v145, v145, v197
	v_lshlrev_b32_e32 v195, 16, v168
	v_and_b32_e32 v197, 0xffff0000, v168
	v_add_f32_e32 v146, v146, v195
	v_add_f32_e32 v147, v147, v197
	v_lshlrev_b32_e32 v195, 16, v169
	v_and_b32_e32 v197, 0xffff0000, v169
	v_add_f32_e32 v148, v148, v195
	v_add_f32_e32 v149, v149, v197
	global_load_dwordx4 v[150:153], v163, s[12:13]
	global_load_dwordx4 v[154:157], v163, s[12:13] offset:16
	global_load_dwordx4 v[158:161], v163, s[12:13] offset:2048
	global_load_dwordx4 v[166:169], v163, s[12:13] offset:2064
	s_waitcnt vmcnt(12)
	v_lshlrev_b32_e32 v195, 16, v170
	v_and_b32_e32 v197, 0xffff0000, v170
	v_add_f32_e32 v118, v118, v195
	v_add_f32_e32 v119, v119, v197
	v_lshlrev_b32_e32 v195, 16, v171
	v_and_b32_e32 v197, 0xffff0000, v171
	v_add_f32_e32 v120, v120, v195
	v_add_f32_e32 v121, v121, v197
	v_lshlrev_b32_e32 v195, 16, v172
	v_and_b32_e32 v197, 0xffff0000, v172
	v_add_f32_e32 v122, v122, v195
	v_add_f32_e32 v123, v123, v197
	v_lshlrev_b32_e32 v195, 16, v173
	v_and_b32_e32 v197, 0xffff0000, v173
	v_add_f32_e32 v124, v124, v195
	v_add_f32_e32 v125, v125, v197
	v_lshlrev_b32_e32 v195, 16, v174
	v_and_b32_e32 v197, 0xffff0000, v174
	v_add_f32_e32 v126, v126, v195
	v_add_f32_e32 v127, v127, v197
	v_lshlrev_b32_e32 v195, 16, v175
	v_and_b32_e32 v197, 0xffff0000, v175
	v_add_f32_e32 v128, v128, v195
	v_add_f32_e32 v129, v129, v197
	v_lshlrev_b32_e32 v195, 16, v176
	v_and_b32_e32 v197, 0xffff0000, v176
	v_add_f32_e32 v130, v130, v195
	v_add_f32_e32 v131, v131, v197
	v_lshlrev_b32_e32 v195, 16, v177
	v_and_b32_e32 v197, 0xffff0000, v177
	v_add_f32_e32 v132, v132, v195
	v_add_f32_e32 v133, v133, v197
	v_lshlrev_b32_e32 v195, 16, v178
	v_and_b32_e32 v197, 0xffff0000, v178
	v_add_f32_e32 v134, v134, v195
	v_add_f32_e32 v135, v135, v197
	v_lshlrev_b32_e32 v195, 16, v179
	v_and_b32_e32 v197, 0xffff0000, v179
	v_add_f32_e32 v136, v136, v195
	v_add_f32_e32 v137, v137, v197
	v_lshlrev_b32_e32 v195, 16, v180
	v_and_b32_e32 v197, 0xffff0000, v180
	v_add_f32_e32 v138, v138, v195
	v_add_f32_e32 v139, v139, v197
	v_lshlrev_b32_e32 v195, 16, v181
	v_and_b32_e32 v197, 0xffff0000, v181
	v_add_f32_e32 v140, v140, v195
	v_add_f32_e32 v141, v141, v197
	v_lshlrev_b32_e32 v195, 16, v182
	v_and_b32_e32 v197, 0xffff0000, v182
	v_add_f32_e32 v142, v142, v195
	v_add_f32_e32 v143, v143, v197
	v_lshlrev_b32_e32 v195, 16, v183
	v_and_b32_e32 v197, 0xffff0000, v183
	v_add_f32_e32 v144, v144, v195
	v_add_f32_e32 v145, v145, v197
	v_lshlrev_b32_e32 v195, 16, v184
	v_and_b32_e32 v197, 0xffff0000, v184
	v_add_f32_e32 v146, v146, v195
	v_add_f32_e32 v147, v147, v197
	v_lshlrev_b32_e32 v195, 16, v185
	v_and_b32_e32 v197, 0xffff0000, v185
	v_add_f32_e32 v148, v148, v195
	v_add_f32_e32 v149, v149, v197
	global_load_dwordx4 v[170:173], v194, s[12:13]
	global_load_dwordx4 v[174:177], v194, s[12:13] offset:16
	global_load_dwordx4 v[178:181], v194, s[12:13] offset:2048
	global_load_dwordx4 v[182:185], v194, s[12:13] offset:2064
	s_waitcnt vmcnt(12)
	v_lshlrev_b32_e32 v195, 16, v186
	v_and_b32_e32 v197, 0xffff0000, v186
	v_add_f32_e32 v118, v118, v195
	v_add_f32_e32 v119, v119, v197
	v_lshlrev_b32_e32 v195, 16, v187
	v_and_b32_e32 v197, 0xffff0000, v187
	v_add_f32_e32 v120, v120, v195
	v_add_f32_e32 v121, v121, v197
	v_lshlrev_b32_e32 v195, 16, v188
	v_and_b32_e32 v197, 0xffff0000, v188
	v_add_f32_e32 v122, v122, v195
	v_add_f32_e32 v123, v123, v197
	v_lshlrev_b32_e32 v195, 16, v189
	v_and_b32_e32 v197, 0xffff0000, v189
	v_add_f32_e32 v124, v124, v195
	v_add_f32_e32 v125, v125, v197
	v_lshlrev_b32_e32 v195, 16, v190
	v_and_b32_e32 v197, 0xffff0000, v190
	v_add_f32_e32 v126, v126, v195
	v_add_f32_e32 v127, v127, v197
	v_lshlrev_b32_e32 v195, 16, v191
	v_and_b32_e32 v197, 0xffff0000, v191
	v_add_f32_e32 v128, v128, v195
	v_add_f32_e32 v129, v129, v197
	v_lshlrev_b32_e32 v195, 16, v192
	v_and_b32_e32 v197, 0xffff0000, v192
	v_add_f32_e32 v130, v130, v195
	v_add_f32_e32 v131, v131, v197
	v_lshlrev_b32_e32 v195, 16, v193
	v_and_b32_e32 v197, 0xffff0000, v193
	v_add_f32_e32 v132, v132, v195
	v_add_f32_e32 v133, v133, v197
	v_lshlrev_b32_e32 v195, 16, v198
	v_and_b32_e32 v197, 0xffff0000, v198
	v_add_f32_e32 v134, v134, v195
	v_add_f32_e32 v135, v135, v197
	v_lshlrev_b32_e32 v195, 16, v199
	v_and_b32_e32 v197, 0xffff0000, v199
	v_add_f32_e32 v136, v136, v195
	v_add_f32_e32 v137, v137, v197
	v_lshlrev_b32_e32 v195, 16, v200
	v_and_b32_e32 v197, 0xffff0000, v200
	v_add_f32_e32 v138, v138, v195
	v_add_f32_e32 v139, v139, v197
	v_lshlrev_b32_e32 v195, 16, v201
	v_and_b32_e32 v197, 0xffff0000, v201
	v_add_f32_e32 v140, v140, v195
	v_add_f32_e32 v141, v141, v197
	v_lshlrev_b32_e32 v195, 16, v202
	v_and_b32_e32 v197, 0xffff0000, v202
	v_add_f32_e32 v142, v142, v195
	v_add_f32_e32 v143, v143, v197
	v_lshlrev_b32_e32 v195, 16, v203
	v_and_b32_e32 v197, 0xffff0000, v203
	v_add_f32_e32 v144, v144, v195
	v_add_f32_e32 v145, v145, v197
	v_lshlrev_b32_e32 v195, 16, v204
	v_and_b32_e32 v197, 0xffff0000, v204
	v_add_f32_e32 v146, v146, v195
	v_add_f32_e32 v147, v147, v197
	v_lshlrev_b32_e32 v195, 16, v205
	v_and_b32_e32 v197, 0xffff0000, v205
	v_add_f32_e32 v148, v148, v195
	v_add_f32_e32 v149, v149, v197
	s_waitcnt vmcnt(8)
	v_lshlrev_b32_e32 v195, 16, v206
	v_and_b32_e32 v197, 0xffff0000, v206
	v_add_f32_e32 v118, v118, v195
	v_add_f32_e32 v119, v119, v197
	v_lshlrev_b32_e32 v195, 16, v207
	v_and_b32_e32 v197, 0xffff0000, v207
	v_add_f32_e32 v120, v120, v195
	v_add_f32_e32 v121, v121, v197
	v_lshlrev_b32_e32 v195, 16, v208
	v_and_b32_e32 v197, 0xffff0000, v208
	v_add_f32_e32 v122, v122, v195
	v_add_f32_e32 v123, v123, v197
	v_lshlrev_b32_e32 v195, 16, v209
	v_and_b32_e32 v197, 0xffff0000, v209
	v_add_f32_e32 v124, v124, v195
	v_add_f32_e32 v125, v125, v197
	v_lshlrev_b32_e32 v195, 16, v210
	v_and_b32_e32 v197, 0xffff0000, v210
	v_add_f32_e32 v126, v126, v195
	v_add_f32_e32 v127, v127, v197
	v_lshlrev_b32_e32 v195, 16, v211
	v_and_b32_e32 v197, 0xffff0000, v211
	v_add_f32_e32 v128, v128, v195
	v_add_f32_e32 v129, v129, v197
	v_lshlrev_b32_e32 v195, 16, v212
	v_and_b32_e32 v197, 0xffff0000, v212
	v_add_f32_e32 v130, v130, v195
	v_add_f32_e32 v131, v131, v197
	v_lshlrev_b32_e32 v195, 16, v213
	v_and_b32_e32 v197, 0xffff0000, v213
	v_add_f32_e32 v132, v132, v195
	v_add_f32_e32 v133, v133, v197
	v_lshlrev_b32_e32 v195, 16, v214
	v_and_b32_e32 v197, 0xffff0000, v214
	v_add_f32_e32 v134, v134, v195
	v_add_f32_e32 v135, v135, v197
	v_lshlrev_b32_e32 v195, 16, v215
	v_and_b32_e32 v197, 0xffff0000, v215
	v_add_f32_e32 v136, v136, v195
	v_add_f32_e32 v137, v137, v197
	v_lshlrev_b32_e32 v195, 16, v216
	v_and_b32_e32 v197, 0xffff0000, v216
	v_add_f32_e32 v138, v138, v195
	v_add_f32_e32 v139, v139, v197
	v_lshlrev_b32_e32 v195, 16, v217
	v_and_b32_e32 v197, 0xffff0000, v217
	v_add_f32_e32 v140, v140, v195
	v_add_f32_e32 v141, v141, v197
	v_lshlrev_b32_e32 v195, 16, v218
	v_and_b32_e32 v197, 0xffff0000, v218
	v_add_f32_e32 v142, v142, v195
	v_add_f32_e32 v143, v143, v197
	v_lshlrev_b32_e32 v195, 16, v219
	v_and_b32_e32 v197, 0xffff0000, v219
	v_add_f32_e32 v144, v144, v195
	v_add_f32_e32 v145, v145, v197
	v_lshlrev_b32_e32 v195, 16, v220
	v_and_b32_e32 v197, 0xffff0000, v220
	v_add_f32_e32 v146, v146, v195
	v_add_f32_e32 v147, v147, v197
	v_lshlrev_b32_e32 v195, 16, v221
	v_and_b32_e32 v197, 0xffff0000, v221
	v_add_f32_e32 v148, v148, v195
	v_add_f32_e32 v149, v149, v197
	s_lshl_b32 s97, s48, 12
	s_add_u32 s94, s34, s97
	s_addc_u32 s95, s35, 0
	s_add_u32 s94, s94, 0x2aa00000
	s_addc_u32 s95, s95, 0
	v_cvt_pk_bf16_f32 v186, v118, v119
	v_cvt_pk_bf16_f32 v187, v120, v121
	v_cvt_pk_bf16_f32 v188, v122, v123
	v_cvt_pk_bf16_f32 v189, v124, v125
	global_store_dwordx4 v162, v[186:189], s[94:95]
	v_cvt_pk_bf16_f32 v190, v126, v127
	v_cvt_pk_bf16_f32 v191, v128, v129
	v_cvt_pk_bf16_f32 v192, v130, v131
	v_cvt_pk_bf16_f32 v193, v132, v133
	global_store_dwordx4 v162, v[190:193], s[94:95] offset:1024
	v_cvt_pk_bf16_f32 v198, v134, v135
	v_cvt_pk_bf16_f32 v199, v136, v137
	v_cvt_pk_bf16_f32 v200, v138, v139
	v_cvt_pk_bf16_f32 v201, v140, v141
	global_store_dwordx4 v162, v[198:201], s[94:95] offset:2048
	v_cvt_pk_bf16_f32 v202, v142, v143
	v_cvt_pk_bf16_f32 v203, v144, v145
	v_cvt_pk_bf16_f32 v204, v146, v147
	v_cvt_pk_bf16_f32 v205, v148, v149
	global_store_dwordx4 v162, v[202:205], s[94:95] offset:3072
	v_lshlrev_b32_e32 v118, 16, v186
	v_and_b32_e32 v119, 0xffff0000, v186
	v_lshlrev_b32_e32 v120, 16, v187
	v_and_b32_e32 v121, 0xffff0000, v187
	v_lshlrev_b32_e32 v122, 16, v188
	v_and_b32_e32 v123, 0xffff0000, v188
	v_lshlrev_b32_e32 v124, 16, v189
	v_and_b32_e32 v125, 0xffff0000, v189
	v_lshlrev_b32_e32 v126, 16, v190
	v_and_b32_e32 v127, 0xffff0000, v190
	v_lshlrev_b32_e32 v128, 16, v191
	v_and_b32_e32 v129, 0xffff0000, v191
	v_lshlrev_b32_e32 v130, 16, v192
	v_and_b32_e32 v131, 0xffff0000, v192
	v_lshlrev_b32_e32 v132, 16, v193
	v_and_b32_e32 v133, 0xffff0000, v193
	v_lshlrev_b32_e32 v134, 16, v198
	v_and_b32_e32 v135, 0xffff0000, v198
	v_lshlrev_b32_e32 v136, 16, v199
	v_and_b32_e32 v137, 0xffff0000, v199
	v_lshlrev_b32_e32 v138, 16, v200
	v_and_b32_e32 v139, 0xffff0000, v200
	v_lshlrev_b32_e32 v140, 16, v201
	v_and_b32_e32 v141, 0xffff0000, v201
	v_lshlrev_b32_e32 v142, 16, v202
	v_and_b32_e32 v143, 0xffff0000, v202
	v_lshlrev_b32_e32 v144, 16, v203
	v_and_b32_e32 v145, 0xffff0000, v203
	v_lshlrev_b32_e32 v146, 16, v204
	v_and_b32_e32 v147, 0xffff0000, v204
	v_lshlrev_b32_e32 v148, 16, v205
	v_and_b32_e32 v149, 0xffff0000, v205
	v_mul_f32_e32 v227, v118, v118
	v_fmac_f32_e32 v227, v119, v119
	v_fmac_f32_e32 v227, v120, v120
	v_fmac_f32_e32 v227, v121, v121
	v_fmac_f32_e32 v227, v122, v122
	v_fmac_f32_e32 v227, v123, v123
	v_fmac_f32_e32 v227, v124, v124
	v_fmac_f32_e32 v227, v125, v125
	v_fmac_f32_e32 v227, v126, v126
	v_fmac_f32_e32 v227, v127, v127
	v_fmac_f32_e32 v227, v128, v128
	v_fmac_f32_e32 v227, v129, v129
	v_fmac_f32_e32 v227, v130, v130
	v_fmac_f32_e32 v227, v131, v131
	v_fmac_f32_e32 v227, v132, v132
	v_fmac_f32_e32 v227, v133, v133
	v_fmac_f32_e32 v227, v134, v134
	v_fmac_f32_e32 v227, v135, v135
	v_fmac_f32_e32 v227, v136, v136
	v_fmac_f32_e32 v227, v137, v137
	v_fmac_f32_e32 v227, v138, v138
	v_fmac_f32_e32 v227, v139, v139
	v_fmac_f32_e32 v227, v140, v140
	v_fmac_f32_e32 v227, v141, v141
	v_fmac_f32_e32 v227, v142, v142
	v_fmac_f32_e32 v227, v143, v143
	v_fmac_f32_e32 v227, v144, v144
	v_fmac_f32_e32 v227, v145, v145
	v_fmac_f32_e32 v227, v146, v146
	v_fmac_f32_e32 v227, v147, v147
	v_fmac_f32_e32 v227, v148, v148
	v_fmac_f32_e32 v227, v149, v149
	v_xor_b32_e32 v195, 4, v243
	ds_bpermute_b32 v242, v195, v227
	s_waitcnt lgkmcnt(0)
	v_add_f32_e32 v227, v227, v242
	v_xor_b32_e32 v195, 8, v243
	ds_bpermute_b32 v242, v195, v227
	s_waitcnt lgkmcnt(0)
	v_add_f32_e32 v227, v227, v242
	v_xor_b32_e32 v195, 16, v243
	ds_bpermute_b32 v242, v195, v227
	s_waitcnt lgkmcnt(0)
	v_add_f32_e32 v227, v227, v242
	v_xor_b32_e32 v195, 32, v243
	ds_bpermute_b32 v242, v195, v227
	s_waitcnt lgkmcnt(0)
	v_add_f32_e32 v227, v227, v242
	v_xor_b32_e32 v195, 64, v243
	ds_bpermute_b32 v242, v195, v227
	s_waitcnt lgkmcnt(0)
	v_add_f32_e32 v227, v227, v242
	v_xor_b32_e32 v195, 128, v243
	ds_bpermute_b32 v242, v195, v227
	s_waitcnt lgkmcnt(0)
	v_add_f32_e32 v227, v227, v242
	v_mov_b32_e32 v240, 0x3a000000
	v_mov_b32_e32 v241, 0x358637bd
	v_fma_f32 v227, v227, v240, v241
	v_rsq_f32_e32 v227, v227
	s_lshl_b32 s97, s48, 12
	s_add_u32 s100, s34, s97
	s_addc_u32 s101, s35, 0
	s_add_u32 s100, s100, 0x9800000
	s_addc_u32 s101, s101, 0
	s_waitcnt vmcnt(4)
	v_mul_f32_e32 v118, v118, v227
	v_mul_f32_e32 v118, v118, v150
	v_mul_f32_e32 v119, v119, v227
	v_mul_f32_e32 v119, v119, v151
	v_mul_f32_e32 v120, v120, v227
	v_mul_f32_e32 v120, v120, v152
	v_mul_f32_e32 v121, v121, v227
	v_mul_f32_e32 v121, v121, v153
	v_mul_f32_e32 v122, v122, v227
	v_mul_f32_e32 v122, v122, v154
	v_mul_f32_e32 v123, v123, v227
	v_mul_f32_e32 v123, v123, v155
	v_mul_f32_e32 v124, v124, v227
	v_mul_f32_e32 v124, v124, v156
	v_mul_f32_e32 v125, v125, v227
	v_mul_f32_e32 v125, v125, v157
	v_mul_f32_e32 v126, v126, v227
	v_mul_f32_e32 v126, v126, v158
	v_mul_f32_e32 v127, v127, v227
	v_mul_f32_e32 v127, v127, v159
	v_mul_f32_e32 v128, v128, v227
	v_mul_f32_e32 v128, v128, v160
	v_mul_f32_e32 v129, v129, v227
	v_mul_f32_e32 v129, v129, v161
	v_mul_f32_e32 v130, v130, v227
	v_mul_f32_e32 v130, v130, v166
	v_mul_f32_e32 v131, v131, v227
	v_mul_f32_e32 v131, v131, v167
	v_mul_f32_e32 v132, v132, v227
	v_mul_f32_e32 v132, v132, v168
	v_mul_f32_e32 v133, v133, v227
	v_mul_f32_e32 v133, v133, v169
	v_mul_f32_e32 v134, v134, v227
	v_mul_f32_e32 v134, v134, v170
	v_mul_f32_e32 v135, v135, v227
	v_mul_f32_e32 v135, v135, v171
	v_mul_f32_e32 v136, v136, v227
	v_mul_f32_e32 v136, v136, v172
	v_mul_f32_e32 v137, v137, v227
	v_mul_f32_e32 v137, v137, v173
	v_mul_f32_e32 v138, v138, v227
	v_mul_f32_e32 v138, v138, v174
	v_mul_f32_e32 v139, v139, v227
	v_mul_f32_e32 v139, v139, v175
	v_mul_f32_e32 v140, v140, v227
	v_mul_f32_e32 v140, v140, v176
	v_mul_f32_e32 v141, v141, v227
	v_mul_f32_e32 v141, v141, v177
	v_mul_f32_e32 v142, v142, v227
	v_mul_f32_e32 v142, v142, v178
	v_mul_f32_e32 v143, v143, v227
	v_mul_f32_e32 v143, v143, v179
	v_mul_f32_e32 v144, v144, v227
	v_mul_f32_e32 v144, v144, v180
	v_mul_f32_e32 v145, v145, v227
	v_mul_f32_e32 v145, v145, v181
	v_mul_f32_e32 v146, v146, v227
	v_mul_f32_e32 v146, v146, v182
	v_mul_f32_e32 v147, v147, v227
	v_mul_f32_e32 v147, v147, v183
	v_mul_f32_e32 v148, v148, v227
	v_mul_f32_e32 v148, v148, v184
	v_mul_f32_e32 v149, v149, v227
	v_mul_f32_e32 v149, v149, v185
	v_cvt_pk_bf16_f32 v206, v118, v119
	v_cvt_pk_bf16_f32 v207, v120, v121
	v_cvt_pk_bf16_f32 v208, v122, v123
	v_cvt_pk_bf16_f32 v209, v124, v125
	global_store_dwordx4 v162, v[206:209], s[100:101]
	v_cvt_pk_bf16_f32 v210, v126, v127
	v_cvt_pk_bf16_f32 v211, v128, v129
	v_cvt_pk_bf16_f32 v212, v130, v131
	v_cvt_pk_bf16_f32 v213, v132, v133
	global_store_dwordx4 v162, v[210:213], s[100:101] offset:1024
	v_cvt_pk_bf16_f32 v214, v134, v135
	v_cvt_pk_bf16_f32 v215, v136, v137
	v_cvt_pk_bf16_f32 v216, v138, v139
	v_cvt_pk_bf16_f32 v217, v140, v141
	global_store_dwordx4 v162, v[214:217], s[100:101] offset:2048
	v_cvt_pk_bf16_f32 v218, v142, v143
	v_cvt_pk_bf16_f32 v219, v144, v145
	v_cvt_pk_bf16_f32 v220, v146, v147
	v_cvt_pk_bf16_f32 v221, v148, v149
	global_store_dwordx4 v162, v[218:221], s[100:101] offset:3072
	s_branch .LBB0_1042
.Lsrow_r2_orig:
	s_add_u32 s3, s34, 0x19600000
	s_addc_u32 s8, s35, 0
	v_mov_b32_e32 v41, 0
	s_and_b64 s[14:15], s[38:39], exec
	v_or_b32_e32 v2, 0x1000, v48
	v_mov_b32_e32 v3, v41
	s_cselect_b32 s15, 0, s8
	s_cselect_b32 s14, 0, s3
	v_mov_b32_e32 v49, v41
	s_waitcnt lgkmcnt(0)
	v_lshl_add_u64 v[46:47], s[12:13], 0, v[2:3]
	v_or_b32_e32 v2, 0x1800, v48
	s_cmp_gt_i32 s26, -1
	v_lshl_add_u64 v[36:37], s[14:15], 0, v[40:41]
	v_lshl_add_u64 v[0:1], s[34:35], 0, v[40:41]
	s_mov_b64 s[14:15], 0x2ca00000
	v_lshl_add_u64 v[42:43], s[6:7], 0, v[40:41]
	v_lshl_add_u64 v[44:45], s[12:13], 0, v[48:49]
	v_lshl_add_u64 v[48:49], s[12:13], 0, v[2:3]
	s_cselect_b64 s[6:7], -1, 0
	s_mov_b64 s[12:13], 0x22200000
	v_lshl_add_u64 v[52:53], s[10:11], 0, v[40:41]
	s_mov_b64 s[10:11], 0x2aa00000
	v_lshl_add_u64 v[38:39], v[0:1], 0, s[14:15]
	v_lshl_add_u64 v[50:51], v[0:1], 0, s[12:13]
	v_lshl_add_u64 v[54:55], v[0:1], 0, s[10:11]
	s_ashr_i32 s19, s18, 31
	v_cndmask_b32_e64 v0, 0, 1, s[6:7]
	s_mov_b32 s9, 0
	s_lshl_b64 s[10:11], s[18:19], 12
	v_cmp_ne_u32_e64 s[6:7], 1, v0
	s_mov_b32 s3, 0x400000
	s_mov_b32 s13, 0x800000
	s_mov_b32 s19, 0xc00000
	s_mov_b32 s25, 0x1000000
	s_mov_b32 s29, 0x1400000
	s_mov_b32 s52, 0x1800000
	s_mov_b32 s53, 0x1c00000
	v_mov_b32_e32 v56, 0x358637bd
	s_mov_b32 s12, 0x3a000000
	s_mov_b32 s54, 0xdee00000
	s_mov_b32 s55, 0xdee00400
	s_mov_b32 s56, 0xdee00800
	s_xor_b64 s[14:15], s[38:39], -1
	s_branch .LBB0_1031

.LBB0_1293:
	s_cmpk_gt_i32 s24, 0x23ff
	s_cbranch_scc1 .LBB0_1307
	s_cmpk_lg_i32 s26, 0x100
	s_cbranch_scc1 .Lsrow_r3_orig
	s_waitcnt lgkmcnt(0)
	v_and_b32_e32 v195, 63, v164
	v_lshlrev_b32_e32 v162, 4, v195
	v_lshlrev_b32_e32 v163, 5, v195
	v_lshlrev_b32_e32 v243, 2, v195
	v_add_u32_e32 v194, 0x1000, v163
	s_add_i32 s93, s24, 0xffffe000
	s_lshl_b32 s97, s93, 12
	s_add_u32 s98, s34, s97
	s_addc_u32 s99, s35, 0
	s_add_u32 s98, s98, 0x19600000
	s_addc_u32 s99, s99, 0
	s_lshl_b32 s97, s24, 12
	s_add_u32 s94, s34, s97
	s_addc_u32 s95, s35, 0
	s_add_u32 s94, s94, 0x2aa00000
	s_addc_u32 s95, s95, 0
	global_load_dwordx4 v[222:225], v162, s[94:95]
	global_load_dwordx4 v[228:231], v162, s[94:95] offset:1024
	global_load_dwordx4 v[232:235], v162, s[94:95] offset:2048
	global_load_dwordx4 v[236:239], v162, s[94:95] offset:3072
	global_load_dwordx4 v[150:153], v162, s[98:99]
	global_load_dwordx4 v[154:157], v162, s[98:99] offset:1024
	global_load_dwordx4 v[158:161], v162, s[98:99] offset:2048
	global_load_dwordx4 v[166:169], v162, s[98:99] offset:3072
	s_add_u32 s98, s98, 0x400000
	s_addc_u32 s99, s99, 0
	global_load_dwordx4 v[170:173], v162, s[98:99]
	global_load_dwordx4 v[174:177], v162, s[98:99] offset:1024
	global_load_dwordx4 v[178:181], v162, s[98:99] offset:2048
	global_load_dwordx4 v[182:185], v162, s[98:99] offset:3072
	s_add_u32 s98, s98, 0x400000
	s_addc_u32 s99, s99, 0
	global_load_dwordx4 v[186:189], v162, s[98:99]
	global_load_dwordx4 v[190:193], v162, s[98:99] offset:1024
	global_load_dwordx4 v[198:201], v162, s[98:99] offset:2048
	global_load_dwordx4 v[202:205], v162, s[98:99] offset:3072
	s_add_u32 s98, s98, 0x400000
	s_addc_u32 s99, s99, 0
	global_load_dwordx4 v[206:209], v162, s[98:99]
	global_load_dwordx4 v[210:213], v162, s[98:99] offset:1024
	global_load_dwordx4 v[214:217], v162, s[98:99] offset:2048
	global_load_dwordx4 v[218:221], v162, s[98:99] offset:3072
	s_add_u32 s98, s98, 0x400000
	s_addc_u32 s99, s99, 0
	s_waitcnt vmcnt(16)
	v_lshlrev_b32_e32 v118, 16, v222
	v_and_b32_e32 v119, 0xffff0000, v222
	v_lshlrev_b32_e32 v120, 16, v223
	v_and_b32_e32 v121, 0xffff0000, v223
	v_lshlrev_b32_e32 v122, 16, v224
	v_and_b32_e32 v123, 0xffff0000, v224
	v_lshlrev_b32_e32 v124, 16, v225
	v_and_b32_e32 v125, 0xffff0000, v225
	v_lshlrev_b32_e32 v126, 16, v228
	v_and_b32_e32 v127, 0xffff0000, v228
	v_lshlrev_b32_e32 v128, 16, v229
	v_and_b32_e32 v129, 0xffff0000, v229
	v_lshlrev_b32_e32 v130, 16, v230
	v_and_b32_e32 v131, 0xffff0000, v230
	v_lshlrev_b32_e32 v132, 16, v231
	v_and_b32_e32 v133, 0xffff0000, v231
	v_lshlrev_b32_e32 v134, 16, v232
	v_and_b32_e32 v135, 0xffff0000, v232
	v_lshlrev_b32_e32 v136, 16, v233
	v_and_b32_e32 v137, 0xffff0000, v233
	v_lshlrev_b32_e32 v138, 16, v234
	v_and_b32_e32 v139, 0xffff0000, v234
	v_lshlrev_b32_e32 v140, 16, v235
	v_and_b32_e32 v141, 0xffff0000, v235
	v_lshlrev_b32_e32 v142, 16, v236
	v_and_b32_e32 v143, 0xffff0000, v236
	v_lshlrev_b32_e32 v144, 16, v237
	v_and_b32_e32 v145, 0xffff0000, v237
	v_lshlrev_b32_e32 v146, 16, v238
	v_and_b32_e32 v147, 0xffff0000, v238
	v_lshlrev_b32_e32 v148, 16, v239
	v_and_b32_e32 v149, 0xffff0000, v239
	s_waitcnt vmcnt(12)
	v_lshlrev_b32_e32 v195, 16, v150
	v_and_b32_e32 v197, 0xffff0000, v150
	v_add_f32_e32 v118, v118, v195
	v_add_f32_e32 v119, v119, v197
	v_lshlrev_b32_e32 v195, 16, v151
	v_and_b32_e32 v197, 0xffff0000, v151
	v_add_f32_e32 v120, v120, v195
	v_add_f32_e32 v121, v121, v197
	v_lshlrev_b32_e32 v195, 16, v152
	v_and_b32_e32 v197, 0xffff0000, v152
	v_add_f32_e32 v122, v122, v195
	v_add_f32_e32 v123, v123, v197
	v_lshlrev_b32_e32 v195, 16, v153
	v_and_b32_e32 v197, 0xffff0000, v153
	v_add_f32_e32 v124, v124, v195
	v_add_f32_e32 v125, v125, v197
	v_lshlrev_b32_e32 v195, 16, v154
	v_and_b32_e32 v197, 0xffff0000, v154
	v_add_f32_e32 v126, v126, v195
	v_add_f32_e32 v127, v127, v197
	v_lshlrev_b32_e32 v195, 16, v155
	v_and_b32_e32 v197, 0xffff0000, v155
	v_add_f32_e32 v128, v128, v195
	v_add_f32_e32 v129, v129, v197
	v_lshlrev_b32_e32 v195, 16, v156
	v_and_b32_e32 v197, 0xffff0000, v156
	v_add_f32_e32 v130, v130, v195
	v_add_f32_e32 v131, v131, v197
	v_lshlrev_b32_e32 v195, 16, v157
	v_and_b32_e32 v197, 0xffff0000, v157
	v_add_f32_e32 v132, v132, v195
	v_add_f32_e32 v133, v133, v197
	v_lshlrev_b32_e32 v195, 16, v158
	v_and_b32_e32 v197, 0xffff0000, v158
	v_add_f32_e32 v134, v134, v195
	v_add_f32_e32 v135, v135, v197
	v_lshlrev_b32_e32 v195, 16, v159
	v_and_b32_e32 v197, 0xffff0000, v159
	v_add_f32_e32 v136, v136, v195
	v_add_f32_e32 v137, v137, v197
	v_lshlrev_b32_e32 v195, 16, v160
	v_and_b32_e32 v197, 0xffff0000, v160
	v_add_f32_e32 v138, v138, v195
	v_add_f32_e32 v139, v139, v197
	v_lshlrev_b32_e32 v195, 16, v161
	v_and_b32_e32 v197, 0xffff0000, v161
	v_add_f32_e32 v140, v140, v195
	v_add_f32_e32 v141, v141, v197
	v_lshlrev_b32_e32 v195, 16, v166
	v_and_b32_e32 v197, 0xffff0000, v166
	v_add_f32_e32 v142, v142, v195
	v_add_f32_e32 v143, v143, v197
	v_lshlrev_b32_e32 v195, 16, v167
	v_and_b32_e32 v197, 0xffff0000, v167
	v_add_f32_e32 v144, v144, v195
	v_add_f32_e32 v145, v145, v197
	v_lshlrev_b32_e32 v195, 16, v168
	v_and_b32_e32 v197, 0xffff0000, v168
	v_add_f32_e32 v146, v146, v195
	v_add_f32_e32 v147, v147, v197
	v_lshlrev_b32_e32 v195, 16, v169
	v_and_b32_e32 v197, 0xffff0000, v169
	v_add_f32_e32 v148, v148, v195
	v_add_f32_e32 v149, v149, v197
	global_load_dwordx4 v[150:153], v162, s[98:99]
	global_load_dwordx4 v[154:157], v162, s[98:99] offset:1024
	global_load_dwordx4 v[158:161], v162, s[98:99] offset:2048
	global_load_dwordx4 v[166:169], v162, s[98:99] offset:3072
	s_add_u32 s98, s98, 0x400000
	s_addc_u32 s99, s99, 0
	s_waitcnt vmcnt(12)
	v_lshlrev_b32_e32 v195, 16, v170
	v_and_b32_e32 v197, 0xffff0000, v170
	v_add_f32_e32 v118, v118, v195
	v_add_f32_e32 v119, v119, v197
	v_lshlrev_b32_e32 v195, 16, v171
	v_and_b32_e32 v197, 0xffff0000, v171
	v_add_f32_e32 v120, v120, v195
	v_add_f32_e32 v121, v121, v197
	v_lshlrev_b32_e32 v195, 16, v172
	v_and_b32_e32 v197, 0xffff0000, v172
	v_add_f32_e32 v122, v122, v195
	v_add_f32_e32 v123, v123, v197
	v_lshlrev_b32_e32 v195, 16, v173
	v_and_b32_e32 v197, 0xffff0000, v173
	v_add_f32_e32 v124, v124, v195
	v_add_f32_e32 v125, v125, v197
	v_lshlrev_b32_e32 v195, 16, v174
	v_and_b32_e32 v197, 0xffff0000, v174
	v_add_f32_e32 v126, v126, v195
	v_add_f32_e32 v127, v127, v197
	v_lshlrev_b32_e32 v195, 16, v175
	v_and_b32_e32 v197, 0xffff0000, v175
	v_add_f32_e32 v128, v128, v195
	v_add_f32_e32 v129, v129, v197
	v_lshlrev_b32_e32 v195, 16, v176
	v_and_b32_e32 v197, 0xffff0000, v176
	v_add_f32_e32 v130, v130, v195
	v_add_f32_e32 v131, v131, v197
	v_lshlrev_b32_e32 v195, 16, v177
	v_and_b32_e32 v197, 0xffff0000, v177
	v_add_f32_e32 v132, v132, v195
	v_add_f32_e32 v133, v133, v197
	v_lshlrev_b32_e32 v195, 16, v178
	v_and_b32_e32 v197, 0xffff0000, v178
	v_add_f32_e32 v134, v134, v195
	v_add_f32_e32 v135, v135, v197
	v_lshlrev_b32_e32 v195, 16, v179
	v_and_b32_e32 v197, 0xffff0000, v179
	v_add_f32_e32 v136, v136, v195
	v_add_f32_e32 v137, v137, v197
	v_lshlrev_b32_e32 v195, 16, v180
	v_and_b32_e32 v197, 0xffff0000, v180
	v_add_f32_e32 v138, v138, v195
	v_add_f32_e32 v139, v139, v197
	v_lshlrev_b32_e32 v195, 16, v181
	v_and_b32_e32 v197, 0xffff0000, v181
	v_add_f32_e32 v140, v140, v195
	v_add_f32_e32 v141, v141, v197
	v_lshlrev_b32_e32 v195, 16, v182
	v_and_b32_e32 v197, 0xffff0000, v182
	v_add_f32_e32 v142, v142, v195
	v_add_f32_e32 v143, v143, v197
	v_lshlrev_b32_e32 v195, 16, v183
	v_and_b32_e32 v197, 0xffff0000, v183
	v_add_f32_e32 v144, v144, v195
	v_add_f32_e32 v145, v145, v197
	v_lshlrev_b32_e32 v195, 16, v184
	v_and_b32_e32 v197, 0xffff0000, v184
	v_add_f32_e32 v146, v146, v195
	v_add_f32_e32 v147, v147, v197
	v_lshlrev_b32_e32 v195, 16, v185
	v_and_b32_e32 v197, 0xffff0000, v185
	v_add_f32_e32 v148, v148, v195
	v_add_f32_e32 v149, v149, v197
	global_load_dwordx4 v[170:173], v162, s[98:99]
	global_load_dwordx4 v[174:177], v162, s[98:99] offset:1024
	global_load_dwordx4 v[178:181], v162, s[98:99] offset:2048
	global_load_dwordx4 v[182:185], v162, s[98:99] offset:3072
	s_add_u32 s98, s98, 0x400000
	s_addc_u32 s99, s99, 0
	s_waitcnt vmcnt(12)
	v_lshlrev_b32_e32 v195, 16, v186
	v_and_b32_e32 v197, 0xffff0000, v186
	v_add_f32_e32 v118, v118, v195
	v_add_f32_e32 v119, v119, v197
	v_lshlrev_b32_e32 v195, 16, v187
	v_and_b32_e32 v197, 0xffff0000, v187
	v_add_f32_e32 v120, v120, v195
	v_add_f32_e32 v121, v121, v197
	v_lshlrev_b32_e32 v195, 16, v188
	v_and_b32_e32 v197, 0xffff0000, v188
	v_add_f32_e32 v122, v122, v195
	v_add_f32_e32 v123, v123, v197
	v_lshlrev_b32_e32 v195, 16, v189
	v_and_b32_e32 v197, 0xffff0000, v189
	v_add_f32_e32 v124, v124, v195
	v_add_f32_e32 v125, v125, v197
	v_lshlrev_b32_e32 v195, 16, v190
	v_and_b32_e32 v197, 0xffff0000, v190
	v_add_f32_e32 v126, v126, v195
	v_add_f32_e32 v127, v127, v197
	v_lshlrev_b32_e32 v195, 16, v191
	v_and_b32_e32 v197, 0xffff0000, v191
	v_add_f32_e32 v128, v128, v195
	v_add_f32_e32 v129, v129, v197
	v_lshlrev_b32_e32 v195, 16, v192
	v_and_b32_e32 v197, 0xffff0000, v192
	v_add_f32_e32 v130, v130, v195
	v_add_f32_e32 v131, v131, v197
	v_lshlrev_b32_e32 v195, 16, v193
	v_and_b32_e32 v197, 0xffff0000, v193
	v_add_f32_e32 v132, v132, v195
	v_add_f32_e32 v133, v133, v197
	v_lshlrev_b32_e32 v195, 16, v198
	v_and_b32_e32 v197, 0xffff0000, v198
	v_add_f32_e32 v134, v134, v195
	v_add_f32_e32 v135, v135, v197
	v_lshlrev_b32_e32 v195, 16, v199
	v_and_b32_e32 v197, 0xffff0000, v199
	v_add_f32_e32 v136, v136, v195
	v_add_f32_e32 v137, v137, v197
	v_lshlrev_b32_e32 v195, 16, v200
	v_and_b32_e32 v197, 0xffff0000, v200
	v_add_f32_e32 v138, v138, v195
	v_add_f32_e32 v139, v139, v197
	v_lshlrev_b32_e32 v195, 16, v201
	v_and_b32_e32 v197, 0xffff0000, v201
	v_add_f32_e32 v140, v140, v195
	v_add_f32_e32 v141, v141, v197
	v_lshlrev_b32_e32 v195, 16, v202
	v_and_b32_e32 v197, 0xffff0000, v202
	v_add_f32_e32 v142, v142, v195
	v_add_f32_e32 v143, v143, v197
	v_lshlrev_b32_e32 v195, 16, v203
	v_and_b32_e32 v197, 0xffff0000, v203
	v_add_f32_e32 v144, v144, v195
	v_add_f32_e32 v145, v145, v197
	v_lshlrev_b32_e32 v195, 16, v204
	v_and_b32_e32 v197, 0xffff0000, v204
	v_add_f32_e32 v146, v146, v195
	v_add_f32_e32 v147, v147, v197
	v_lshlrev_b32_e32 v195, 16, v205
	v_and_b32_e32 v197, 0xffff0000, v205
	v_add_f32_e32 v148, v148, v195
	v_add_f32_e32 v149, v149, v197
	global_load_dwordx4 v[186:189], v162, s[98:99]
	global_load_dwordx4 v[190:193], v162, s[98:99] offset:1024
	global_load_dwordx4 v[198:201], v162, s[98:99] offset:2048
	global_load_dwordx4 v[202:205], v162, s[98:99] offset:3072
	s_add_u32 s98, s98, 0x400000
	s_addc_u32 s99, s99, 0
	s_waitcnt vmcnt(12)
	v_lshlrev_b32_e32 v195, 16, v206
	v_and_b32_e32 v197, 0xffff0000, v206
	v_add_f32_e32 v118, v118, v195
	v_add_f32_e32 v119, v119, v197
	v_lshlrev_b32_e32 v195, 16, v207
	v_and_b32_e32 v197, 0xffff0000, v207
	v_add_f32_e32 v120, v120, v195
	v_add_f32_e32 v121, v121, v197
	v_lshlrev_b32_e32 v195, 16, v208
	v_and_b32_e32 v197, 0xffff0000, v208
	v_add_f32_e32 v122, v122, v195
	v_add_f32_e32 v123, v123, v197
	v_lshlrev_b32_e32 v195, 16, v209
	v_and_b32_e32 v197, 0xffff0000, v209
	v_add_f32_e32 v124, v124, v195
	v_add_f32_e32 v125, v125, v197
	v_lshlrev_b32_e32 v195, 16, v210
	v_and_b32_e32 v197, 0xffff0000, v210
	v_add_f32_e32 v126, v126, v195
	v_add_f32_e32 v127, v127, v197
	v_lshlrev_b32_e32 v195, 16, v211
	v_and_b32_e32 v197, 0xffff0000, v211
	v_add_f32_e32 v128, v128, v195
	v_add_f32_e32 v129, v129, v197
	v_lshlrev_b32_e32 v195, 16, v212
	v_and_b32_e32 v197, 0xffff0000, v212
	v_add_f32_e32 v130, v130, v195
	v_add_f32_e32 v131, v131, v197
	v_lshlrev_b32_e32 v195, 16, v213
	v_and_b32_e32 v197, 0xffff0000, v213
	v_add_f32_e32 v132, v132, v195
	v_add_f32_e32 v133, v133, v197
	v_lshlrev_b32_e32 v195, 16, v214
	v_and_b32_e32 v197, 0xffff0000, v214
	v_add_f32_e32 v134, v134, v195
	v_add_f32_e32 v135, v135, v197
	v_lshlrev_b32_e32 v195, 16, v215
	v_and_b32_e32 v197, 0xffff0000, v215
	v_add_f32_e32 v136, v136, v195
	v_add_f32_e32 v137, v137, v197
	v_lshlrev_b32_e32 v195, 16, v216
	v_and_b32_e32 v197, 0xffff0000, v216
	v_add_f32_e32 v138, v138, v195
	v_add_f32_e32 v139, v139, v197
	v_lshlrev_b32_e32 v195, 16, v217
	v_and_b32_e32 v197, 0xffff0000, v217
	v_add_f32_e32 v140, v140, v195
	v_add_f32_e32 v141, v141, v197
	v_lshlrev_b32_e32 v195, 16, v218
	v_and_b32_e32 v197, 0xffff0000, v218
	v_add_f32_e32 v142, v142, v195
	v_add_f32_e32 v143, v143, v197
	v_lshlrev_b32_e32 v195, 16, v219
	v_and_b32_e32 v197, 0xffff0000, v219
	v_add_f32_e32 v144, v144, v195
	v_add_f32_e32 v145, v145, v197
	v_lshlrev_b32_e32 v195, 16, v220
	v_and_b32_e32 v197, 0xffff0000, v220
	v_add_f32_e32 v146, v146, v195
	v_add_f32_e32 v147, v147, v197
	v_lshlrev_b32_e32 v195, 16, v221
	v_and_b32_e32 v197, 0xffff0000, v221
	v_add_f32_e32 v148, v148, v195
	v_add_f32_e32 v149, v149, v197
	global_load_dwordx4 v[206:209], v162, s[98:99]
	global_load_dwordx4 v[210:213], v162, s[98:99] offset:1024
	global_load_dwordx4 v[214:217], v162, s[98:99] offset:2048
	global_load_dwordx4 v[218:221], v162, s[98:99] offset:3072
	s_add_u32 s98, s98, 0x400000
	s_addc_u32 s99, s99, 0
	s_waitcnt vmcnt(12)
	v_lshlrev_b32_e32 v195, 16, v150
	v_and_b32_e32 v197, 0xffff0000, v150
	v_add_f32_e32 v118, v118, v195
	v_add_f32_e32 v119, v119, v197
	v_lshlrev_b32_e32 v195, 16, v151
	v_and_b32_e32 v197, 0xffff0000, v151
	v_add_f32_e32 v120, v120, v195
	v_add_f32_e32 v121, v121, v197
	v_lshlrev_b32_e32 v195, 16, v152
	v_and_b32_e32 v197, 0xffff0000, v152
	v_add_f32_e32 v122, v122, v195
	v_add_f32_e32 v123, v123, v197
	v_lshlrev_b32_e32 v195, 16, v153
	v_and_b32_e32 v197, 0xffff0000, v153
	v_add_f32_e32 v124, v124, v195
	v_add_f32_e32 v125, v125, v197
	v_lshlrev_b32_e32 v195, 16, v154
	v_and_b32_e32 v197, 0xffff0000, v154
	v_add_f32_e32 v126, v126, v195
	v_add_f32_e32 v127, v127, v197
	v_lshlrev_b32_e32 v195, 16, v155
	v_and_b32_e32 v197, 0xffff0000, v155
	v_add_f32_e32 v128, v128, v195
	v_add_f32_e32 v129, v129, v197
	v_lshlrev_b32_e32 v195, 16, v156
	v_and_b32_e32 v197, 0xffff0000, v156
	v_add_f32_e32 v130, v130, v195
	v_add_f32_e32 v131, v131, v197
	v_lshlrev_b32_e32 v195, 16, v157
	v_and_b32_e32 v197, 0xffff0000, v157
	v_add_f32_e32 v132, v132, v195
	v_add_f32_e32 v133, v133, v197
	v_lshlrev_b32_e32 v195, 16, v158
	v_and_b32_e32 v197, 0xffff0000, v158
	v_add_f32_e32 v134, v134, v195
	v_add_f32_e32 v135, v135, v197
	v_lshlrev_b32_e32 v195, 16, v159
	v_and_b32_e32 v197, 0xffff0000, v159
	v_add_f32_e32 v136, v136, v195
	v_add_f32_e32 v137, v137, v197
	v_lshlrev_b32_e32 v195, 16, v160
	v_and_b32_e32 v197, 0xffff0000, v160
	v_add_f32_e32 v138, v138, v195
	v_add_f32_e32 v139, v139, v197
	v_lshlrev_b32_e32 v195, 16, v161
	v_and_b32_e32 v197, 0xffff0000, v161
	v_add_f32_e32 v140, v140, v195
	v_add_f32_e32 v141, v141, v197
	v_lshlrev_b32_e32 v195, 16, v166
	v_and_b32_e32 v197, 0xffff0000, v166
	v_add_f32_e32 v142, v142, v195
	v_add_f32_e32 v143, v143, v197
	v_lshlrev_b32_e32 v195, 16, v167
	v_and_b32_e32 v197, 0xffff0000, v167
	v_add_f32_e32 v144, v144, v195
	v_add_f32_e32 v145, v145, v197
	v_lshlrev_b32_e32 v195, 16, v168
	v_and_b32_e32 v197, 0xffff0000, v168
	v_add_f32_e32 v146, v146, v195
	v_add_f32_e32 v147, v147, v197
	v_lshlrev_b32_e32 v195, 16, v169
	v_and_b32_e32 v197, 0xffff0000, v169
	v_add_f32_e32 v148, v148, v195
	v_add_f32_e32 v149, v149, v197
	global_load_dwordx4 v[150:153], v163, s[0:1]
	global_load_dwordx4 v[154:157], v163, s[0:1] offset:16
	global_load_dwordx4 v[158:161], v163, s[0:1] offset:2048
	global_load_dwordx4 v[166:169], v163, s[0:1] offset:2064
	s_waitcnt vmcnt(12)
	v_lshlrev_b32_e32 v195, 16, v170
	v_and_b32_e32 v197, 0xffff0000, v170
	v_add_f32_e32 v118, v118, v195
	v_add_f32_e32 v119, v119, v197
	v_lshlrev_b32_e32 v195, 16, v171
	v_and_b32_e32 v197, 0xffff0000, v171
	v_add_f32_e32 v120, v120, v195
	v_add_f32_e32 v121, v121, v197
	v_lshlrev_b32_e32 v195, 16, v172
	v_and_b32_e32 v197, 0xffff0000, v172
	v_add_f32_e32 v122, v122, v195
	v_add_f32_e32 v123, v123, v197
	v_lshlrev_b32_e32 v195, 16, v173
	v_and_b32_e32 v197, 0xffff0000, v173
	v_add_f32_e32 v124, v124, v195
	v_add_f32_e32 v125, v125, v197
	v_lshlrev_b32_e32 v195, 16, v174
	v_and_b32_e32 v197, 0xffff0000, v174
	v_add_f32_e32 v126, v126, v195
	v_add_f32_e32 v127, v127, v197
	v_lshlrev_b32_e32 v195, 16, v175
	v_and_b32_e32 v197, 0xffff0000, v175
	v_add_f32_e32 v128, v128, v195
	v_add_f32_e32 v129, v129, v197
	v_lshlrev_b32_e32 v195, 16, v176
	v_and_b32_e32 v197, 0xffff0000, v176
	v_add_f32_e32 v130, v130, v195
	v_add_f32_e32 v131, v131, v197
	v_lshlrev_b32_e32 v195, 16, v177
	v_and_b32_e32 v197, 0xffff0000, v177
	v_add_f32_e32 v132, v132, v195
	v_add_f32_e32 v133, v133, v197
	v_lshlrev_b32_e32 v195, 16, v178
	v_and_b32_e32 v197, 0xffff0000, v178
	v_add_f32_e32 v134, v134, v195
	v_add_f32_e32 v135, v135, v197
	v_lshlrev_b32_e32 v195, 16, v179
	v_and_b32_e32 v197, 0xffff0000, v179
	v_add_f32_e32 v136, v136, v195
	v_add_f32_e32 v137, v137, v197
	v_lshlrev_b32_e32 v195, 16, v180
	v_and_b32_e32 v197, 0xffff0000, v180
	v_add_f32_e32 v138, v138, v195
	v_add_f32_e32 v139, v139, v197
	v_lshlrev_b32_e32 v195, 16, v181
	v_and_b32_e32 v197, 0xffff0000, v181
	v_add_f32_e32 v140, v140, v195
	v_add_f32_e32 v141, v141, v197
	v_lshlrev_b32_e32 v195, 16, v182
	v_and_b32_e32 v197, 0xffff0000, v182
	v_add_f32_e32 v142, v142, v195
	v_add_f32_e32 v143, v143, v197
	v_lshlrev_b32_e32 v195, 16, v183
	v_and_b32_e32 v197, 0xffff0000, v183
	v_add_f32_e32 v144, v144, v195
	v_add_f32_e32 v145, v145, v197
	v_lshlrev_b32_e32 v195, 16, v184
	v_and_b32_e32 v197, 0xffff0000, v184
	v_add_f32_e32 v146, v146, v195
	v_add_f32_e32 v147, v147, v197
	v_lshlrev_b32_e32 v195, 16, v185
	v_and_b32_e32 v197, 0xffff0000, v185
	v_add_f32_e32 v148, v148, v195
	v_add_f32_e32 v149, v149, v197
	global_load_dwordx4 v[170:173], v194, s[0:1]
	global_load_dwordx4 v[174:177], v194, s[0:1] offset:16
	global_load_dwordx4 v[178:181], v194, s[0:1] offset:2048
	global_load_dwordx4 v[182:185], v194, s[0:1] offset:2064
	s_waitcnt vmcnt(12)
	v_lshlrev_b32_e32 v195, 16, v186
	v_and_b32_e32 v197, 0xffff0000, v186
	v_add_f32_e32 v118, v118, v195
	v_add_f32_e32 v119, v119, v197
	v_lshlrev_b32_e32 v195, 16, v187
	v_and_b32_e32 v197, 0xffff0000, v187
	v_add_f32_e32 v120, v120, v195
	v_add_f32_e32 v121, v121, v197
	v_lshlrev_b32_e32 v195, 16, v188
	v_and_b32_e32 v197, 0xffff0000, v188
	v_add_f32_e32 v122, v122, v195
	v_add_f32_e32 v123, v123, v197
	v_lshlrev_b32_e32 v195, 16, v189
	v_and_b32_e32 v197, 0xffff0000, v189
	v_add_f32_e32 v124, v124, v195
	v_add_f32_e32 v125, v125, v197
	v_lshlrev_b32_e32 v195, 16, v190
	v_and_b32_e32 v197, 0xffff0000, v190
	v_add_f32_e32 v126, v126, v195
	v_add_f32_e32 v127, v127, v197
	v_lshlrev_b32_e32 v195, 16, v191
	v_and_b32_e32 v197, 0xffff0000, v191
	v_add_f32_e32 v128, v128, v195
	v_add_f32_e32 v129, v129, v197
	v_lshlrev_b32_e32 v195, 16, v192
	v_and_b32_e32 v197, 0xffff0000, v192
	v_add_f32_e32 v130, v130, v195
	v_add_f32_e32 v131, v131, v197
	v_lshlrev_b32_e32 v195, 16, v193
	v_and_b32_e32 v197, 0xffff0000, v193
	v_add_f32_e32 v132, v132, v195
	v_add_f32_e32 v133, v133, v197
	v_lshlrev_b32_e32 v195, 16, v198
	v_and_b32_e32 v197, 0xffff0000, v198
	v_add_f32_e32 v134, v134, v195
	v_add_f32_e32 v135, v135, v197
	v_lshlrev_b32_e32 v195, 16, v199
	v_and_b32_e32 v197, 0xffff0000, v199
	v_add_f32_e32 v136, v136, v195
	v_add_f32_e32 v137, v137, v197
	v_lshlrev_b32_e32 v195, 16, v200
	v_and_b32_e32 v197, 0xffff0000, v200
	v_add_f32_e32 v138, v138, v195
	v_add_f32_e32 v139, v139, v197
	v_lshlrev_b32_e32 v195, 16, v201
	v_and_b32_e32 v197, 0xffff0000, v201
	v_add_f32_e32 v140, v140, v195
	v_add_f32_e32 v141, v141, v197
	v_lshlrev_b32_e32 v195, 16, v202
	v_and_b32_e32 v197, 0xffff0000, v202
	v_add_f32_e32 v142, v142, v195
	v_add_f32_e32 v143, v143, v197
	v_lshlrev_b32_e32 v195, 16, v203
	v_and_b32_e32 v197, 0xffff0000, v203
	v_add_f32_e32 v144, v144, v195
	v_add_f32_e32 v145, v145, v197
	v_lshlrev_b32_e32 v195, 16, v204
	v_and_b32_e32 v197, 0xffff0000, v204
	v_add_f32_e32 v146, v146, v195
	v_add_f32_e32 v147, v147, v197
	v_lshlrev_b32_e32 v195, 16, v205
	v_and_b32_e32 v197, 0xffff0000, v205
	v_add_f32_e32 v148, v148, v195
	v_add_f32_e32 v149, v149, v197
	s_waitcnt vmcnt(8)
	v_lshlrev_b32_e32 v195, 16, v206
	v_and_b32_e32 v197, 0xffff0000, v206
	v_add_f32_e32 v118, v118, v195
	v_add_f32_e32 v119, v119, v197
	v_lshlrev_b32_e32 v195, 16, v207
	v_and_b32_e32 v197, 0xffff0000, v207
	v_add_f32_e32 v120, v120, v195
	v_add_f32_e32 v121, v121, v197
	v_lshlrev_b32_e32 v195, 16, v208
	v_and_b32_e32 v197, 0xffff0000, v208
	v_add_f32_e32 v122, v122, v195
	v_add_f32_e32 v123, v123, v197
	v_lshlrev_b32_e32 v195, 16, v209
	v_and_b32_e32 v197, 0xffff0000, v209
	v_add_f32_e32 v124, v124, v195
	v_add_f32_e32 v125, v125, v197
	v_lshlrev_b32_e32 v195, 16, v210
	v_and_b32_e32 v197, 0xffff0000, v210
	v_add_f32_e32 v126, v126, v195
	v_add_f32_e32 v127, v127, v197
	v_lshlrev_b32_e32 v195, 16, v211
	v_and_b32_e32 v197, 0xffff0000, v211
	v_add_f32_e32 v128, v128, v195
	v_add_f32_e32 v129, v129, v197
	v_lshlrev_b32_e32 v195, 16, v212
	v_and_b32_e32 v197, 0xffff0000, v212
	v_add_f32_e32 v130, v130, v195
	v_add_f32_e32 v131, v131, v197
	v_lshlrev_b32_e32 v195, 16, v213
	v_and_b32_e32 v197, 0xffff0000, v213
	v_add_f32_e32 v132, v132, v195
	v_add_f32_e32 v133, v133, v197
	v_lshlrev_b32_e32 v195, 16, v214
	v_and_b32_e32 v197, 0xffff0000, v214
	v_add_f32_e32 v134, v134, v195
	v_add_f32_e32 v135, v135, v197
	v_lshlrev_b32_e32 v195, 16, v215
	v_and_b32_e32 v197, 0xffff0000, v215
	v_add_f32_e32 v136, v136, v195
	v_add_f32_e32 v137, v137, v197
	v_lshlrev_b32_e32 v195, 16, v216
	v_and_b32_e32 v197, 0xffff0000, v216
	v_add_f32_e32 v138, v138, v195
	v_add_f32_e32 v139, v139, v197
	v_lshlrev_b32_e32 v195, 16, v217
	v_and_b32_e32 v197, 0xffff0000, v217
	v_add_f32_e32 v140, v140, v195
	v_add_f32_e32 v141, v141, v197
	v_lshlrev_b32_e32 v195, 16, v218
	v_and_b32_e32 v197, 0xffff0000, v218
	v_add_f32_e32 v142, v142, v195
	v_add_f32_e32 v143, v143, v197
	v_lshlrev_b32_e32 v195, 16, v219
	v_and_b32_e32 v197, 0xffff0000, v219
	v_add_f32_e32 v144, v144, v195
	v_add_f32_e32 v145, v145, v197
	v_lshlrev_b32_e32 v195, 16, v220
	v_and_b32_e32 v197, 0xffff0000, v220
	v_add_f32_e32 v146, v146, v195
	v_add_f32_e32 v147, v147, v197
	v_lshlrev_b32_e32 v195, 16, v221
	v_and_b32_e32 v197, 0xffff0000, v221
	v_add_f32_e32 v148, v148, v195
	v_add_f32_e32 v149, v149, v197
	v_mul_f32_e32 v227, v118, v118
	v_fmac_f32_e32 v227, v119, v119
	v_fmac_f32_e32 v227, v120, v120
	v_fmac_f32_e32 v227, v121, v121
	v_fmac_f32_e32 v227, v122, v122
	v_fmac_f32_e32 v227, v123, v123
	v_fmac_f32_e32 v227, v124, v124
	v_fmac_f32_e32 v227, v125, v125
	v_fmac_f32_e32 v227, v126, v126
	v_fmac_f32_e32 v227, v127, v127
	v_fmac_f32_e32 v227, v128, v128
	v_fmac_f32_e32 v227, v129, v129
	v_fmac_f32_e32 v227, v130, v130
	v_fmac_f32_e32 v227, v131, v131
	v_fmac_f32_e32 v227, v132, v132
	v_fmac_f32_e32 v227, v133, v133
	v_fmac_f32_e32 v227, v134, v134
	v_fmac_f32_e32 v227, v135, v135
	v_fmac_f32_e32 v227, v136, v136
	v_fmac_f32_e32 v227, v137, v137
	v_fmac_f32_e32 v227, v138, v138
	v_fmac_f32_e32 v227, v139, v139
	v_fmac_f32_e32 v227, v140, v140
	v_fmac_f32_e32 v227, v141, v141
	v_fmac_f32_e32 v227, v142, v142
	v_fmac_f32_e32 v227, v143, v143
	v_fmac_f32_e32 v227, v144, v144
	v_fmac_f32_e32 v227, v145, v145
	v_fmac_f32_e32 v227, v146, v146
	v_fmac_f32_e32 v227, v147, v147
	v_fmac_f32_e32 v227, v148, v148
	v_fmac_f32_e32 v227, v149, v149
	v_xor_b32_e32 v195, 4, v243
	ds_bpermute_b32 v242, v195, v227
	s_waitcnt lgkmcnt(0)
	v_add_f32_e32 v227, v227, v242
	v_xor_b32_e32 v195, 8, v243
	ds_bpermute_b32 v242, v195, v227
	s_waitcnt lgkmcnt(0)
	v_add_f32_e32 v227, v227, v242
	v_xor_b32_e32 v195, 16, v243
	ds_bpermute_b32 v242, v195, v227
	s_waitcnt lgkmcnt(0)
	v_add_f32_e32 v227, v227, v242
	v_xor_b32_e32 v195, 32, v243
	ds_bpermute_b32 v242, v195, v227
	s_waitcnt lgkmcnt(0)
	v_add_f32_e32 v227, v227, v242
	v_xor_b32_e32 v195, 64, v243
	ds_bpermute_b32 v242, v195, v227
	s_waitcnt lgkmcnt(0)
	v_add_f32_e32 v227, v227, v242
	v_xor_b32_e32 v195, 128, v243
	ds_bpermute_b32 v242, v195, v227
	s_waitcnt lgkmcnt(0)
	v_add_f32_e32 v227, v227, v242
	v_mov_b32_e32 v240, 0x3a000000
	v_mov_b32_e32 v241, 0x358637bd
	v_fma_f32 v227, v227, v240, v241
	v_rsq_f32_e32 v227, v227
	s_lshl_b32 s97, s24, 13
	s_add_u32 s100, s20, s97
	s_addc_u32 s101, s21, 0
	s_waitcnt vmcnt(0)
	v_mul_f32_e32 v118, v118, v227
	v_mul_f32_e32 v118, v118, v150
	v_mul_f32_e32 v119, v119, v227
	v_mul_f32_e32 v119, v119, v151
	v_mul_f32_e32 v120, v120, v227
	v_mul_f32_e32 v120, v120, v152
	v_mul_f32_e32 v121, v121, v227
	v_mul_f32_e32 v121, v121, v153
	v_mul_f32_e32 v122, v122, v227
	v_mul_f32_e32 v122, v122, v154
	v_mul_f32_e32 v123, v123, v227
	v_mul_f32_e32 v123, v123, v155
	v_mul_f32_e32 v124, v124, v227
	v_mul_f32_e32 v124, v124, v156
	v_mul_f32_e32 v125, v125, v227
	v_mul_f32_e32 v125, v125, v157
	v_mul_f32_e32 v126, v126, v227
	v_mul_f32_e32 v126, v126, v158
	v_mul_f32_e32 v127, v127, v227
	v_mul_f32_e32 v127, v127, v159
	v_mul_f32_e32 v128, v128, v227
	v_mul_f32_e32 v128, v128, v160
	v_mul_f32_e32 v129, v129, v227
	v_mul_f32_e32 v129, v129, v161
	v_mul_f32_e32 v130, v130, v227
	v_mul_f32_e32 v130, v130, v166
	v_mul_f32_e32 v131, v131, v227
	v_mul_f32_e32 v131, v131, v167
	v_mul_f32_e32 v132, v132, v227
	v_mul_f32_e32 v132, v132, v168
	v_mul_f32_e32 v133, v133, v227
	v_mul_f32_e32 v133, v133, v169
	v_mul_f32_e32 v134, v134, v227
	v_mul_f32_e32 v134, v134, v170
	v_mul_f32_e32 v135, v135, v227
	v_mul_f32_e32 v135, v135, v171
	v_mul_f32_e32 v136, v136, v227
	v_mul_f32_e32 v136, v136, v172
	v_mul_f32_e32 v137, v137, v227
	v_mul_f32_e32 v137, v137, v173
	v_mul_f32_e32 v138, v138, v227
	v_mul_f32_e32 v138, v138, v174
	v_mul_f32_e32 v139, v139, v227
	v_mul_f32_e32 v139, v139, v175
	v_mul_f32_e32 v140, v140, v227
	v_mul_f32_e32 v140, v140, v176
	v_mul_f32_e32 v141, v141, v227
	v_mul_f32_e32 v141, v141, v177
	v_mul_f32_e32 v142, v142, v227
	v_mul_f32_e32 v142, v142, v178
	v_mul_f32_e32 v143, v143, v227
	v_mul_f32_e32 v143, v143, v179
	v_mul_f32_e32 v144, v144, v227
	v_mul_f32_e32 v144, v144, v180
	v_mul_f32_e32 v145, v145, v227
	v_mul_f32_e32 v145, v145, v181
	v_mul_f32_e32 v146, v146, v227
	v_mul_f32_e32 v146, v146, v182
	v_mul_f32_e32 v147, v147, v227
	v_mul_f32_e32 v147, v147, v183
	v_mul_f32_e32 v148, v148, v227
	v_mul_f32_e32 v148, v148, v184
	v_mul_f32_e32 v149, v149, v227
	v_mul_f32_e32 v149, v149, v185
	global_store_dwordx4 v163, v[118:121], s[100:101]
	global_store_dwordx4 v163, v[122:125], s[100:101] offset:16
	global_store_dwordx4 v163, v[126:129], s[100:101] offset:2048
	global_store_dwordx4 v163, v[130:133], s[100:101] offset:2064
	global_store_dwordx4 v194, v[134:137], s[100:101]
	global_store_dwordx4 v194, v[138:141], s[100:101] offset:16
	global_store_dwordx4 v194, v[142:145], s[100:101] offset:2048
	global_store_dwordx4 v194, v[146:149], s[100:101] offset:2064
	s_branch .LBB0_1307
.Lsrow_r3_orig:
	v_lshlrev_b32_e32 v0, 3, v114
	v_mov_b32_e32 v137, 0
	v_or_b32_e32 v2, 0x400, v0
	s_add_u32 s4, s34, 0x19600000
	v_lshlrev_b32_e32 v4, 2, v2
	v_mov_b32_e32 v5, v137
	s_addc_u32 s8, s35, 0
	s_waitcnt lgkmcnt(0)
	v_lshl_add_u64 v[144:145], s[0:1], 0, v[4:5]
	v_or_b32_e32 v4, 0x600, v0
	s_and_b64 s[6:7], s[38:39], exec
	v_lshlrev_b32_e32 v6, 2, v4
	v_mov_b32_e32 v7, v137
	s_cselect_b32 s7, 0, s8
	s_cselect_b32 s6, 0, s4
	v_lshl_add_u64 v[140:141], s[2:3], 0, v[136:137]
	v_mov_b32_e32 v41, v137
	v_lshl_add_u64 v[146:147], s[0:1], 0, v[6:7]
	s_cmp_gt_i32 s26, -1
	v_lshl_add_u64 v[6:7], s[34:35], 0, v[136:137]
	s_mov_b64 s[2:3], 0x2ca00000
	v_lshl_add_u64 v[142:143], s[0:1], 0, v[40:41]
	s_cselect_b64 s[0:1], -1, 0
	v_lshl_add_u64 v[148:149], v[6:7], 0, s[2:3]
	s_mov_b64 s[2:3], 0x2aa00000
	v_lshl_add_u64 v[150:151], v[6:7], 0, s[2:3]
	s_ashr_i32 s19, s18, 31
	v_lshl_add_u64 v[6:7], s[20:21], 0, v[40:41]
	s_mov_b64 s[2:3], 0x1000
	v_cndmask_b32_e64 v1, 0, 1, s[0:1]
	v_lshlrev_b32_e32 v156, 2, v0
	v_and_b32_e32 v0, 64, v196
	s_mov_b32 s5, 0
	v_lshl_add_u64 v[138:139], s[6:7], 0, v[136:137]
	s_lshl_b64 s[6:7], s[18:19], 12
	v_lshl_add_u64 v[152:153], v[6:7], 0, s[2:3]
	s_lshl_b64 s[8:9], s[18:19], 13
	v_cmp_ne_u32_e64 s[0:1], 1, v1
	s_mov_b32 s11, 0x400000
	s_mov_b32 s19, 0x800000
	s_mov_b32 s26, 0xc00000
	s_mov_b32 s27, 0x1000000
	s_mov_b32 s28, 0x1400000
	s_mov_b32 s29, 0x1800000
	s_mov_b32 s30, 0x1c00000
	v_mov_b32_e32 v154, 0x358637bd
	s_mov_b32 s10, 0x3a000000
	s_movk_i32 s31, 0xf000
	s_movk_i32 s33, 0xf010
	s_movk_i32 s34, 0xf800
	s_movk_i32 s35, 0xf810
	v_lshlrev_b32_e32 v158, 2, v2
	v_lshlrev_b32_e32 v160, 2, v4
	v_add_u32_e32 v155, 64, v0
	v_xor_b32_e32 v197, 1, v196
	v_xor_b32_e32 v198, 2, v196
	v_xor_b32_e32 v199, 4, v196
	v_xor_b32_e32 v200, 8, v196
	v_xor_b32_e32 v201, 16, v196
	v_xor_b32_e32 v202, 32, v196
	s_xor_b64 s[12:13], s[38:39], -1
	s_branch .LBB0_1296

	.amdhsa_kernel _Z14fwd_megakernel4Args
		.amdhsa_group_segment_fixed_size 0
		.amdhsa_private_segment_fixed_size 0
		.amdhsa_kernarg_size 480
		.amdhsa_user_sgpr_count 2
		.amdhsa_user_sgpr_dispatch_ptr 0
		.amdhsa_user_sgpr_queue_ptr 0
		.amdhsa_user_sgpr_kernarg_segment_ptr 1
		.amdhsa_user_sgpr_dispatch_id 0
		.amdhsa_user_sgpr_kernarg_preload_length 0
		.amdhsa_user_sgpr_kernarg_preload_offset 0
		.amdhsa_user_sgpr_private_segment_size 0
		.amdhsa_uses_dynamic_stack 0
		.amdhsa_enable_private_segment 0
		.amdhsa_system_sgpr_workgroup_id_x 1
		.amdhsa_system_sgpr_workgroup_id_y 0
		.amdhsa_system_sgpr_workgroup_id_z 0
		.amdhsa_system_sgpr_workgroup_info 0
		.amdhsa_system_vgpr_workitem_id 2
		.amdhsa_next_free_vgpr 256
		.amdhsa_next_free_sgpr 102
		.amdhsa_accum_offset 256
		.amdhsa_reserve_vcc 1
		.amdhsa_float_round_mode_32 0
		.amdhsa_float_round_mode_16_64 0
		.amdhsa_float_denorm_mode_32 3
		.amdhsa_float_denorm_mode_16_64 3
		.amdhsa_dx10_clamp 1
		.amdhsa_ieee_mode 1
		.amdhsa_fp16_overflow 0
		.amdhsa_tg_split 0
		.amdhsa_exception_fp_ieee_invalid_op 0
		.amdhsa_exception_fp_denorm_src 0
		.amdhsa_exception_fp_ieee_div_zero 0
		.amdhsa_exception_fp_ieee_overflow 0
		.amdhsa_exception_fp_ieee_underflow 0
		.amdhsa_exception_fp_ieee_inexact 0
		.amdhsa_exception_int_div_zero 0
	.end_amdhsa_kernel

amdhsa.kernels:
  - .agpr_count:     0
    .args:
      - .offset:         0
        .size:           224
        .value_kind:     by_value
      - .offset:         224
        .size:           4
        .value_kind:     hidden_block_count_x
      - .offset:         228
        .size:           4
        .value_kind:     hidden_block_count_y
      - .offset:         232
        .size:           4
        .value_kind:     hidden_block_count_z
      - .offset:         236
        .size:           2
        .value_kind:     hidden_group_size_x
      - .offset:         238
        .size:           2
        .value_kind:     hidden_group_size_y
      - .offset:         240
        .size:           2
        .value_kind:     hidden_group_size_z
      - .offset:         242
        .size:           2
        .value_kind:     hidden_remainder_x
      - .offset:         244
        .size:           2
        .value_kind:     hidden_remainder_y
      - .offset:         246
        .size:           2
        .value_kind:     hidden_remainder_z
      - .offset:         264
        .size:           8
        .value_kind:     hidden_global_offset_x
      - .offset:         272
        .size:           8
        .value_kind:     hidden_global_offset_y
      - .offset:         280
        .size:           8
        .value_kind:     hidden_global_offset_z
      - .offset:         288
        .size:           2
        .value_kind:     hidden_grid_dims
      - .offset:         312
        .size:           8
        .value_kind:     hidden_multigrid_sync_arg
      - .offset:         344
        .size:           4
        .value_kind:     hidden_dynamic_lds_size
    .group_segment_fixed_size: 0
    .kernarg_segment_align: 8
    .kernarg_segment_size: 480
    .language:       OpenCL C
    .language_version:
      - 2
      - 0
    .max_flat_workgroup_size: 512
    .name:           _Z14fwd_megakernel4Args
    .private_segment_fixed_size: 0
    .sgpr_count:     108
    .sgpr_spill_count: 15
    .symbol:         _Z14fwd_megakernel4Args.kd
    .uniform_work_group_size: 1
    .uses_dynamic_stack: false
    .vgpr_count:     256
    .vgpr_spill_count: 0
    .wavefront_size: 64
